# nt hint also on converted-weight stores and on the final RMSNorm pass (xb loads, f32 output stores)
# baseline (speedup 1.0000x reference)
.LBB0_12:
	s_waitcnt vmcnt(0)
	v_mul_f32_e32 v6, v6, v18
	v_bfe_u32 v10, v6, 17, 1
	v_mul_f32_e32 v2, v2, v19
	v_add3_u32 v6, v6, v10, s86
	v_bfe_u32 v10, v2, 17, 1
	v_add3_u32 v2, v2, v10, s86
	v_and_b32_e32 v2, 0xfffe0000, v2
	v_and_b32_e32 v6, 0xfffe0000, v6
	v_cvt_pk_bf16_f32 v2, v6, v2
	ds_write_b32 v38, v2 offset:4128
	v_mul_f32_e32 v2, v7, v18
	v_bfe_u32 v6, v2, 17, 1
	v_mul_f32_e32 v3, v3, v19
	v_add3_u32 v2, v2, v6, s86
	v_bfe_u32 v6, v3, 17, 1
	v_and_b32_e32 v2, 0xfffe0000, v2
	v_add3_u32 v3, v3, v6, s86
	v_and_b32_e32 v3, 0xfffe0000, v3
	v_cvt_pk_bf16_f32 v2, v2, v3
	ds_write_b32 v38, v2 offset:4256
	v_mul_f32_e32 v2, v8, v18
	v_bfe_u32 v3, v2, 17, 1
	v_add3_u32 v2, v2, v3, s86
	v_mul_f32_e32 v3, v4, v19
	v_bfe_u32 v4, v3, 17, 1
	v_and_b32_e32 v2, 0xfffe0000, v2
	v_add3_u32 v3, v3, v4, s86
	v_and_b32_e32 v3, 0xfffe0000, v3
	v_cvt_pk_bf16_f32 v2, v2, v3
	ds_write_b32 v38, v2 offset:4384
	v_mul_f32_e32 v2, v9, v18
	v_bfe_u32 v3, v2, 17, 1
	v_add3_u32 v2, v2, v3, s86
	v_mul_f32_e32 v3, v5, v19
	v_bfe_u32 v4, v3, 17, 1
	v_and_b32_e32 v2, 0xfffe0000, v2
	v_add3_u32 v3, v3, v4, s86
	v_and_b32_e32 v3, 0xfffe0000, v3
	v_cvt_pk_bf16_f32 v2, v2, v3
	ds_write_b32 v38, v2 offset:4512
	s_lshl_b32 s42, s44, 7
	s_waitcnt lgkmcnt(0)
	v_add_u32_e32 v26, 0x400, v146
	ds_read2_b32 v[16:17], v146 offset1:8
	ds_read2_b32 v[4:5], v146 offset0:129 offset1:137
	ds_read2_b32 v[18:19], v26 offset0:2 offset1:10
	ds_read2_b32 v[6:7], v26 offset0:131 offset1:139
	v_or_b32_e32 v27, s42, v131
	v_or_b32_e32 v12, v27, v145
	v_ashrrev_i32_e32 v13, 31, v12
	s_sext_i32_i16 s2, s38
	v_lshlrev_b32_e32 v132, 1, v134
	v_mad_i64_i32 v[12:13], s[4:5], s2, v191, v[12:13]
	v_lshl_add_u64 v[2:3], s[40:41], 0, v[132:133]
	v_lshlrev_b64 v[12:13], 7, v[12:13]
	s_waitcnt lgkmcnt(3)
	v_mov_b32_e32 v8, v16
	s_waitcnt lgkmcnt(2)
	v_mov_b32_e32 v9, v4
	s_waitcnt lgkmcnt(1)
	v_mov_b32_e32 v10, v18
	s_waitcnt lgkmcnt(0)
	v_mov_b32_e32 v11, v6
	v_lshl_add_u64 v[12:13], v[2:3], 0, v[12:13]
	global_store_dwordx4 v[12:13], v[8:11], off nt
	v_add_u32_e32 v28, 0x400, v147
	ds_read2_b32 v[20:21], v147 offset1:8
	ds_read2_b32 v[8:9], v147 offset0:129 offset1:137
	ds_read2_b32 v[22:23], v28 offset0:2 offset1:10
	ds_read2_b32 v[10:11], v28 offset0:131 offset1:139
	v_or_b32_e32 v29, s42, v144
	v_or_b32_e32 v24, v29, v145
	v_ashrrev_i32_e32 v25, 31, v24
	v_mad_i64_i32 v[24:25], s[4:5], s2, v191, v[24:25]
	v_lshlrev_b64 v[24:25], 7, v[24:25]
	s_waitcnt lgkmcnt(3)
	v_mov_b32_e32 v12, v20
	s_waitcnt lgkmcnt(2)
	v_mov_b32_e32 v13, v8
	s_waitcnt lgkmcnt(1)
	v_mov_b32_e32 v14, v22
	s_waitcnt lgkmcnt(0)
	v_mov_b32_e32 v15, v10
	v_lshl_add_u64 v[24:25], v[2:3], 0, v[24:25]
	v_add_u32_e32 v4, 0x400, v149
	global_store_dwordx4 v[24:25], v[12:15], off nt
	ds_read2_b32 v[12:13], v149 offset1:129
	ds_read2_b32 v[14:15], v4 offset0:2 offset1:131
	v_or_b32_e32 v24, v27, v148
	v_ashrrev_i32_e32 v25, 31, v24
	v_mad_i64_i32 v[24:25], s[4:5], s2, v191, v[24:25]
	v_lshlrev_b64 v[24:25], 7, v[24:25]
	v_lshl_add_u64 v[24:25], v[2:3], 0, v[24:25]
	v_add_u32_e32 v4, 0x400, v150
	s_waitcnt lgkmcnt(0)
	global_store_dwordx4 v[24:25], v[12:15], off nt
	ds_read2_b32 v[12:13], v150 offset1:129
	ds_read2_b32 v[14:15], v4 offset0:2 offset1:131
	v_or_b32_e32 v24, v29, v148
	v_ashrrev_i32_e32 v25, 31, v24
	v_mad_i64_i32 v[24:25], s[4:5], s2, v191, v[24:25]
	v_lshlrev_b64 v[24:25], 7, v[24:25]
	v_lshl_add_u64 v[24:25], v[2:3], 0, v[24:25]
	s_waitcnt lgkmcnt(0)
	global_store_dwordx4 v[24:25], v[12:15], off nt
	v_mov_b32_e32 v4, v17
	v_mov_b32_e32 v6, v19
	v_or_b32_e32 v12, v27, v151
	v_ashrrev_i32_e32 v13, 31, v12
	v_mad_i64_i32 v[12:13], s[4:5], s2, v191, v[12:13]
	v_lshlrev_b64 v[12:13], 7, v[12:13]
	v_lshl_add_u64 v[12:13], v[2:3], 0, v[12:13]
	global_store_dwordx4 v[12:13], v[4:7], off nt
	v_mov_b32_e32 v8, v21
	v_mov_b32_e32 v10, v23
	v_or_b32_e32 v4, v29, v151
	v_ashrrev_i32_e32 v5, 31, v4
	v_mad_i64_i32 v[4:5], s[4:5], s2, v191, v[4:5]
	v_lshlrev_b64 v[4:5], 7, v[4:5]
	v_lshl_add_u64 v[4:5], v[2:3], 0, v[4:5]
	v_add_u32_e32 v6, 0x400, v153
	global_store_dwordx4 v[4:5], v[8:11], off nt
	ds_read2_b32 v[4:5], v153 offset1:129
	ds_read2_b32 v[6:7], v6 offset0:2 offset1:131
	v_or_b32_e32 v8, v27, v152
	v_ashrrev_i32_e32 v9, 31, v8
	v_mad_i64_i32 v[8:9], s[4:5], s2, v191, v[8:9]
	v_lshlrev_b64 v[8:9], 7, v[8:9]
	v_lshl_add_u64 v[8:9], v[2:3], 0, v[8:9]
	s_waitcnt lgkmcnt(0)
	global_store_dwordx4 v[8:9], v[4:7], off nt
	ds_read2_b32 v[4:5], v154 offset1:129
	v_or_b32_e32 v8, v29, v152
	v_add_u32_e32 v6, 0x400, v154
	ds_read2_b32 v[6:7], v6 offset0:2 offset1:131
	v_ashrrev_i32_e32 v9, 31, v8
	v_mad_i64_i32 v[8:9], s[4:5], s2, v191, v[8:9]
	v_lshlrev_b64 v[8:9], 7, v[8:9]
	v_lshl_add_u64 v[8:9], v[2:3], 0, v[8:9]
	s_waitcnt lgkmcnt(0)
	global_store_dwordx4 v[8:9], v[4:7], off nt
	ds_read2_b32 v[16:17], v146 offset0:16 offset1:24
	ds_read2_b32 v[4:5], v146 offset0:145 offset1:153
	ds_read2_b32 v[18:19], v26 offset0:18 offset1:26
	ds_read2_b32 v[6:7], v26 offset0:147 offset1:155
	v_or_b32_e32 v12, v27, v155
	v_ashrrev_i32_e32 v13, 31, v12
	v_mad_i64_i32 v[12:13], s[4:5], s2, v191, v[12:13]
	v_lshlrev_b64 v[12:13], 7, v[12:13]
	s_waitcnt lgkmcnt(3)
	v_mov_b32_e32 v8, v16
	s_waitcnt lgkmcnt(2)
	v_mov_b32_e32 v9, v4
	s_waitcnt lgkmcnt(1)
	v_mov_b32_e32 v10, v18
	s_waitcnt lgkmcnt(0)
	v_mov_b32_e32 v11, v6
	v_lshl_add_u64 v[12:13], v[2:3], 0, v[12:13]
	global_store_dwordx4 v[12:13], v[8:11], off nt
	ds_read2_b32 v[20:21], v147 offset0:16 offset1:24
	ds_read2_b32 v[8:9], v147 offset0:145 offset1:153
	ds_read2_b32 v[22:23], v28 offset0:18 offset1:26
	ds_read2_b32 v[10:11], v28 offset0:147 offset1:155
	v_or_b32_e32 v24, v29, v155
	v_ashrrev_i32_e32 v25, 31, v24
	v_mad_i64_i32 v[24:25], s[4:5], s2, v191, v[24:25]
	v_lshlrev_b64 v[24:25], 7, v[24:25]
	s_waitcnt lgkmcnt(3)
	v_mov_b32_e32 v12, v20
	s_waitcnt lgkmcnt(2)
	v_mov_b32_e32 v13, v8
	s_waitcnt lgkmcnt(1)
	v_mov_b32_e32 v14, v22
	s_waitcnt lgkmcnt(0)
	v_mov_b32_e32 v15, v10
	v_lshl_add_u64 v[24:25], v[2:3], 0, v[24:25]
	v_add_u32_e32 v4, 0x400, v159
	global_store_dwordx4 v[24:25], v[12:15], off nt
	ds_read2_b32 v[12:13], v159 offset1:129
	ds_read2_b32 v[14:15], v4 offset0:2 offset1:131
	v_or_b32_e32 v24, v27, v158
	v_ashrrev_i32_e32 v25, 31, v24
	v_mad_i64_i32 v[24:25], s[4:5], s2, v191, v[24:25]
	v_lshlrev_b64 v[24:25], 7, v[24:25]
	v_lshl_add_u64 v[24:25], v[2:3], 0, v[24:25]
	v_add_u32_e32 v4, 0x400, v160
	s_waitcnt lgkmcnt(0)
	global_store_dwordx4 v[24:25], v[12:15], off nt
	ds_read2_b32 v[12:13], v160 offset1:129
	ds_read2_b32 v[14:15], v4 offset0:2 offset1:131
	v_or_b32_e32 v24, v29, v158
	v_ashrrev_i32_e32 v25, 31, v24
	v_mad_i64_i32 v[24:25], s[4:5], s2, v191, v[24:25]
	v_lshlrev_b64 v[24:25], 7, v[24:25]
	v_lshl_add_u64 v[24:25], v[2:3], 0, v[24:25]
	s_waitcnt lgkmcnt(0)
	global_store_dwordx4 v[24:25], v[12:15], off nt
	v_mov_b32_e32 v4, v17
	v_mov_b32_e32 v6, v19
	v_or_b32_e32 v12, v27, v161
	v_ashrrev_i32_e32 v13, 31, v12
	v_mad_i64_i32 v[12:13], s[4:5], s2, v191, v[12:13]
	v_lshlrev_b64 v[12:13], 7, v[12:13]
	v_lshl_add_u64 v[12:13], v[2:3], 0, v[12:13]
	global_store_dwordx4 v[12:13], v[4:7], off nt
	v_mov_b32_e32 v8, v21
	v_mov_b32_e32 v10, v23
	v_or_b32_e32 v4, v29, v161
	v_ashrrev_i32_e32 v5, 31, v4
	v_mad_i64_i32 v[4:5], s[4:5], s2, v191, v[4:5]
	v_lshlrev_b64 v[4:5], 7, v[4:5]
	v_lshl_add_u64 v[4:5], v[2:3], 0, v[4:5]
	v_add_u32_e32 v6, 0x400, v163
	global_store_dwordx4 v[4:5], v[8:11], off nt
	ds_read2_b32 v[4:5], v163 offset1:129
	ds_read2_b32 v[6:7], v6 offset0:2 offset1:131
	v_or_b32_e32 v8, v27, v162
	v_ashrrev_i32_e32 v9, 31, v8
	v_mad_i64_i32 v[8:9], s[4:5], s2, v191, v[8:9]
	v_lshlrev_b64 v[8:9], 7, v[8:9]
	v_lshl_add_u64 v[8:9], v[2:3], 0, v[8:9]
	s_waitcnt lgkmcnt(0)
	global_store_dwordx4 v[8:9], v[4:7], off nt
	ds_read2_b32 v[4:5], v164 offset1:129
	v_or_b32_e32 v8, v29, v162
	v_add_u32_e32 v6, 0x400, v164
	ds_read2_b32 v[6:7], v6 offset0:2 offset1:131
	v_ashrrev_i32_e32 v9, 31, v8
	v_mad_i64_i32 v[8:9], s[4:5], s2, v191, v[8:9]
	v_lshlrev_b64 v[8:9], 7, v[8:9]
	v_lshl_add_u64 v[2:3], v[2:3], 0, v[8:9]
	s_waitcnt lgkmcnt(0)
	global_store_dwordx4 v[2:3], v[4:7], off nt
	s_waitcnt lgkmcnt(0)

.LBB0_14:
	v_readlane_b32 s2, v247, 0
	v_readlane_b32 s4, v247, 1
	v_readlane_b32 s5, v247, 2
	v_readlane_b32 s42, v247, 3
	s_nop 0
	s_cmp_ge_i32 s100, s2
	s_cselect_b32 s43, 1, 0
	s_cselect_b32 s2, s2, 0
	s_sub_i32 s2, s100, s2
	v_readlane_b32 s41, v247, 9
	v_readlane_b32 s40, v247, 8
	s_nop 0
	s_cmp_lt_i32 s2, s41
	s_cselect_b32 s5, s5, s40
	s_cmpk_lt_i32 s2, 0xb00
	s_cselect_b32 s4, s4, s5
	s_add_i32 s2, s2, s4
	s_add_i32 s42, s42, s43
	s_mulk_i32 s42, 0x2680
	s_add_i32 s69, s2, s42
	s_lshl_b32 s46, s69, 7
	s_mul_hi_i32 s2, s69, 0x3531dec1
	s_lshr_b32 s4, s2, 31
	s_ashr_i32 s2, s2, 11
	s_add_i32 s42, s2, s4
	s_mul_i32 s2, s42, 0xffffd980
	s_add_i32 s70, s69, s2
	s_ashr_i32 s43, s42, 31
	s_mul_i32 s4, s42, 0x9a00000
	s_mul_hi_i32 s2, s42, 0x9a00000
	s_add_u32 s40, s3, s4
	s_addc_u32 s41, s33, s2
	s_cmpk_gt_i32 s70, 0xaff
	s_mov_b64 s[4:5], -1
	s_cbranch_scc0 .LBB0_96
	s_cmpk_gt_u32 s70, 0x15ff
	s_cbranch_scc0 .LBB0_61
	s_cmpk_gt_u32 s70, 0x197f
	s_cbranch_scc0 .LBB0_26
	s_cmpk_gt_u32 s70, 0x1eff
	s_cbranch_scc0 .LBB0_23
	s_and_b32 s44, s46, 0x780
	s_cmpk_gt_u32 s70, 0x247f
	s_cbranch_scc0 .LBB0_20
	s_lshl_b64 s[4:5], s[42:43], 24
	s_add_u32 s4, s16, s4
	s_addc_u32 s5, s17, s5
	s_add_i32 s2, s70, 0xdb80
	s_bfe_u32 s2, s2, 0xc0004
	v_lshlrev_b32_e32 v2, 2, v135
	v_lshl_or_b32 v132, s2, 19, v2
	v_lshl_add_u64 v[2:3], s[4:5], 0, v[132:133]
	s_lshl_b32 s38, s44, 2
	v_lshl_add_u64 v[2:3], v[2:3], 0, s[38:39]
	v_lshlrev_b32_e32 v132, 2, v130
	v_lshl_add_u64 v[2:3], v[2:3], 0, v[132:133]
	v_add_co_u32_e32 v4, vcc, s68, v2
	s_mov_b32 s4, 0x8000
	s_nop 0
	v_addc_co_u32_e32 v5, vcc, 0, v3, vcc
	global_load_dwordx4 v[106:109], v[2:3], off nt
	global_load_dwordx4 v[110:113], v[4:5], off nt
	v_add_co_u32_e32 v4, vcc, s4, v2
	s_mov_b32 s4, 0xa000
	s_nop 0
	v_addc_co_u32_e32 v5, vcc, 0, v3, vcc
	v_add_co_u32_e32 v6, vcc, s4, v2
	s_mov_b32 s4, 0x10000
	s_nop 0
	v_addc_co_u32_e32 v7, vcc, 0, v3, vcc
	global_load_dwordx4 v[114:117], v[4:5], off nt
	global_load_dwordx4 v[118:121], v[6:7], off nt
	v_add_co_u32_e32 v4, vcc, s4, v2
	s_mov_b32 s4, 0x12000
	s_nop 0
	v_addc_co_u32_e32 v5, vcc, 0, v3, vcc
	v_add_co_u32_e32 v6, vcc, s4, v2
	s_mov_b32 s4, 0x18000
	s_nop 0
	v_addc_co_u32_e32 v7, vcc, 0, v3, vcc
	global_load_dwordx4 v[122:125], v[4:5], off nt
	global_load_dwordx4 v[126:129], v[6:7], off nt
	v_add_co_u32_e32 v4, vcc, s4, v2
	s_mov_b32 s4, 0x1a000
	s_nop 0
	v_addc_co_u32_e32 v5, vcc, 0, v3, vcc
	v_add_co_u32_e32 v6, vcc, s4, v2
	s_mov_b32 s4, 0x20000
	s_nop 0
	v_addc_co_u32_e32 v7, vcc, 0, v3, vcc
	global_load_dwordx4 v[98:101], v[4:5], off nt
	global_load_dwordx4 v[102:105], v[6:7], off nt
	v_add_co_u32_e32 v4, vcc, s4, v2
	s_mov_b32 s4, 0x22000
	s_nop 0
	v_addc_co_u32_e32 v5, vcc, 0, v3, vcc
	v_add_co_u32_e32 v6, vcc, s4, v2
	s_mov_b32 s4, 0x28000
	s_nop 0
	v_addc_co_u32_e32 v7, vcc, 0, v3, vcc
	global_load_dwordx4 v[90:93], v[4:5], off nt
	global_load_dwordx4 v[94:97], v[6:7], off nt
	v_add_co_u32_e32 v4, vcc, s4, v2
	s_mov_b32 s4, 0x30000
	s_nop 0
	v_addc_co_u32_e32 v5, vcc, 0, v3, vcc
	v_add_co_u32_e32 v6, vcc, s58, v2
	s_lshl_b32 s2, s2, 11
	s_nop 0
	v_addc_co_u32_e32 v7, vcc, 0, v3, vcc
	global_load_dwordx4 v[82:85], v[4:5], off nt
	global_load_dwordx4 v[86:89], v[6:7], off nt
	v_add_co_u32_e32 v4, vcc, s4, v2
	s_mov_b32 s4, 0x32000
	s_nop 0
	v_addc_co_u32_e32 v5, vcc, 0, v3, vcc
	v_add_co_u32_e32 v6, vcc, s4, v2
	s_mov_b32 s4, 0x3a000
	s_nop 0
	v_addc_co_u32_e32 v7, vcc, 0, v3, vcc
	global_load_dwordx4 v[74:77], v[4:5], off nt
	global_load_dwordx4 v[78:81], v[6:7], off nt
	v_add_co_u32_e32 v4, vcc, s61, v2
	s_waitcnt vmcnt(13)
	v_bfe_u32 v132, v106, 17, 1
	v_addc_co_u32_e32 v5, vcc, 0, v3, vcc
	v_add_co_u32_e32 v6, vcc, s4, v2
	s_mov_b32 s4, 0x40000
	s_nop 0
	v_addc_co_u32_e32 v7, vcc, 0, v3, vcc
	global_load_dwordx4 v[66:69], v[4:5], off nt
	global_load_dwordx4 v[70:73], v[6:7], off nt
	v_add_co_u32_e32 v4, vcc, s4, v2
	s_mov_b32 s4, 0x42000
	s_nop 0
	v_addc_co_u32_e32 v5, vcc, 0, v3, vcc
	v_add_co_u32_e32 v6, vcc, s4, v2
	s_mov_b32 s4, 0x48000
	s_nop 0
	v_addc_co_u32_e32 v7, vcc, 0, v3, vcc
	global_load_dwordx4 v[58:61], v[4:5], off nt
	global_load_dwordx4 v[62:65], v[6:7], off nt
	v_add_co_u32_e32 v4, vcc, s4, v2
	s_mov_b32 s4, 0x4a000
	s_nop 0
	v_addc_co_u32_e32 v5, vcc, 0, v3, vcc
	v_add_co_u32_e32 v6, vcc, s4, v2
	s_mov_b32 s4, 0x50000
	s_nop 0
	v_addc_co_u32_e32 v7, vcc, 0, v3, vcc
	global_load_dwordx4 v[50:53], v[4:5], off nt
	global_load_dwordx4 v[54:57], v[6:7], off nt
	v_add_co_u32_e32 v4, vcc, s4, v2
	v_add3_u32 v106, v106, v132, s86
	s_nop 0
	v_addc_co_u32_e32 v5, vcc, 0, v3, vcc
	v_add_co_u32_e32 v6, vcc, s75, v2
	s_waitcnt vmcnt(18)
	v_bfe_u32 v132, v110, 17, 1
	v_addc_co_u32_e32 v7, vcc, 0, v3, vcc
	global_load_dwordx4 v[42:45], v[4:5], off nt
	global_load_dwordx4 v[46:49], v[6:7], off nt
	v_add_co_u32_e32 v4, vcc, s76, v2
	v_add3_u32 v110, v110, v132, s86
	s_nop 0
	v_addc_co_u32_e32 v5, vcc, 0, v3, vcc
	v_add_co_u32_e32 v6, vcc, s77, v2
	v_and_b32_e32 v106, 0xfffe0000, v106
	s_nop 0
	v_addc_co_u32_e32 v7, vcc, 0, v3, vcc
	global_load_dwordx4 v[34:37], v[4:5], off nt
	global_load_dwordx4 v[38:41], v[6:7], off nt
	v_add_co_u32_e32 v4, vcc, s78, v2
	v_and_b32_e32 v110, 0xfffe0000, v110
	s_nop 0
	v_addc_co_u32_e32 v5, vcc, 0, v3, vcc
	v_add_co_u32_e32 v6, vcc, s79, v2
	v_lshlrev_b32_e32 v132, 1, v134
	s_nop 0
	v_addc_co_u32_e32 v7, vcc, 0, v3, vcc
	global_load_dwordx4 v[26:29], v[4:5], off nt
	global_load_dwordx4 v[30:33], v[6:7], off nt
	v_add_co_u32_e32 v4, vcc, s80, v2
	s_mov_b64 s[4:5], 0x5000000
	s_nop 0
	v_addc_co_u32_e32 v5, vcc, 0, v3, vcc
	v_add_co_u32_e32 v6, vcc, s81, v2
	s_nop 1
	v_addc_co_u32_e32 v7, vcc, 0, v3, vcc
	global_load_dwordx4 v[18:21], v[4:5], off nt
	global_load_dwordx4 v[22:25], v[6:7], off nt
	v_add_co_u32_e32 v4, vcc, s82, v2
	s_nop 1
	v_addc_co_u32_e32 v5, vcc, 0, v3, vcc
	v_add_co_u32_e32 v6, vcc, s83, v2
	s_nop 1
	v_addc_co_u32_e32 v7, vcc, 0, v3, vcc
	global_load_dwordx4 v[10:13], v[4:5], off nt
	global_load_dwordx4 v[14:17], v[6:7], off nt
	v_add_co_u32_e32 v4, vcc, s84, v2
	s_nop 1
	v_addc_co_u32_e32 v5, vcc, 0, v3, vcc
	v_add_co_u32_e32 v6, vcc, s85, v2
	s_nop 1
	v_addc_co_u32_e32 v7, vcc, 0, v3, vcc
	global_load_dwordx4 v[2:5], v[4:5], off nt
	s_nop 0
	global_load_dwordx4 v[6:9], v[6:7], off nt
	v_cvt_pk_bf16_f32 v106, v106, v110
	v_add_u32_e32 v110, v142, v143
	ds_write_b32 v110, v106
	v_bfe_u32 v106, v107, 17, 1
	v_add3_u32 v106, v107, v106, s86
	v_bfe_u32 v107, v111, 17, 1
	v_and_b32_e32 v106, 0xfffe0000, v106
	v_add3_u32 v107, v111, v107, s86
	v_and_b32_e32 v107, 0xfffe0000, v107
	v_cvt_pk_bf16_f32 v106, v106, v107
	ds_write_b32 v110, v106 offset:128
	v_bfe_u32 v106, v108, 17, 1
	v_add3_u32 v106, v108, v106, s86
	v_bfe_u32 v107, v112, 17, 1
	v_and_b32_e32 v106, 0xfffe0000, v106
	v_add3_u32 v107, v112, v107, s86
	v_and_b32_e32 v107, 0xfffe0000, v107
	v_cvt_pk_bf16_f32 v106, v106, v107
	ds_write_b32 v110, v106 offset:256
	v_bfe_u32 v106, v109, 17, 1
	v_add3_u32 v106, v109, v106, s86
	v_bfe_u32 v107, v113, 17, 1
	v_and_b32_e32 v106, 0xfffe0000, v106
	v_add3_u32 v107, v113, v107, s86
	v_and_b32_e32 v107, 0xfffe0000, v107
	v_cvt_pk_bf16_f32 v106, v106, v107
	ds_write_b32 v110, v106 offset:384
	s_waitcnt vmcnt(29)
	v_bfe_u32 v106, v114, 17, 1
	v_add3_u32 v106, v114, v106, s86
	s_waitcnt vmcnt(28)
	v_bfe_u32 v107, v118, 17, 1
	v_and_b32_e32 v106, 0xfffe0000, v106
	v_add3_u32 v107, v118, v107, s86
	v_and_b32_e32 v107, 0xfffe0000, v107
	v_cvt_pk_bf16_f32 v106, v106, v107
	ds_write_b32 v110, v106 offset:1032
	v_bfe_u32 v106, v115, 17, 1
	v_add3_u32 v106, v115, v106, s86
	v_bfe_u32 v107, v119, 17, 1
	v_and_b32_e32 v106, 0xfffe0000, v106
	v_add3_u32 v107, v119, v107, s86
	v_and_b32_e32 v107, 0xfffe0000, v107
	v_cvt_pk_bf16_f32 v106, v106, v107
	ds_write_b32 v110, v106 offset:1160
	v_bfe_u32 v106, v116, 17, 1
	v_add3_u32 v106, v116, v106, s86
	v_bfe_u32 v107, v120, 17, 1
	v_and_b32_e32 v106, 0xfffe0000, v106
	v_add3_u32 v107, v120, v107, s86
	v_and_b32_e32 v107, 0xfffe0000, v107
	v_cvt_pk_bf16_f32 v106, v106, v107
	ds_write_b32 v110, v106 offset:1288
	v_bfe_u32 v106, v117, 17, 1
	v_add3_u32 v106, v117, v106, s86
	v_bfe_u32 v107, v121, 17, 1
	v_and_b32_e32 v106, 0xfffe0000, v106
	v_add3_u32 v107, v121, v107, s86
	v_and_b32_e32 v107, 0xfffe0000, v107
	v_cvt_pk_bf16_f32 v106, v106, v107
	ds_write_b32 v110, v106 offset:1416
	s_waitcnt vmcnt(27)
	v_bfe_u32 v106, v122, 17, 1
	v_add3_u32 v106, v122, v106, s86
	s_waitcnt vmcnt(26)
	v_bfe_u32 v107, v126, 17, 1
	v_and_b32_e32 v106, 0xfffe0000, v106
	v_add3_u32 v107, v126, v107, s86
	v_and_b32_e32 v107, 0xfffe0000, v107
	v_cvt_pk_bf16_f32 v106, v106, v107
	ds_write_b32 v110, v106 offset:2064
	v_bfe_u32 v106, v123, 17, 1
	v_add3_u32 v106, v123, v106, s86
	v_bfe_u32 v107, v127, 17, 1
	v_and_b32_e32 v106, 0xfffe0000, v106
	v_add3_u32 v107, v127, v107, s86
	v_and_b32_e32 v107, 0xfffe0000, v107
	v_cvt_pk_bf16_f32 v106, v106, v107
	ds_write_b32 v110, v106 offset:2192
	v_bfe_u32 v106, v124, 17, 1
	v_add3_u32 v106, v124, v106, s86
	v_bfe_u32 v107, v128, 17, 1
	v_and_b32_e32 v106, 0xfffe0000, v106
	v_add3_u32 v107, v128, v107, s86
	v_and_b32_e32 v107, 0xfffe0000, v107
	v_cvt_pk_bf16_f32 v106, v106, v107
	ds_write_b32 v110, v106 offset:2320
	v_bfe_u32 v106, v125, 17, 1
	v_add3_u32 v106, v125, v106, s86
	v_bfe_u32 v107, v129, 17, 1
	v_and_b32_e32 v106, 0xfffe0000, v106
	v_add3_u32 v107, v129, v107, s86
	v_and_b32_e32 v107, 0xfffe0000, v107
	v_cvt_pk_bf16_f32 v106, v106, v107
	ds_write_b32 v110, v106 offset:2448
	s_waitcnt vmcnt(25)
	v_bfe_u32 v106, v98, 17, 1
	v_add3_u32 v98, v98, v106, s86
	s_waitcnt vmcnt(24)
	v_bfe_u32 v106, v102, 17, 1
	v_and_b32_e32 v98, 0xfffe0000, v98
	v_add3_u32 v102, v102, v106, s86
	v_and_b32_e32 v102, 0xfffe0000, v102
	v_cvt_pk_bf16_f32 v98, v98, v102
	ds_write_b32 v110, v98 offset:3096
	v_bfe_u32 v98, v99, 17, 1
	v_add3_u32 v98, v99, v98, s86
	v_bfe_u32 v99, v103, 17, 1
	v_and_b32_e32 v98, 0xfffe0000, v98
	v_add3_u32 v99, v103, v99, s86
	v_and_b32_e32 v99, 0xfffe0000, v99
	v_cvt_pk_bf16_f32 v98, v98, v99
	ds_write_b32 v110, v98 offset:3224
	v_bfe_u32 v98, v100, 17, 1
	v_add3_u32 v98, v100, v98, s86
	v_bfe_u32 v99, v104, 17, 1
	v_and_b32_e32 v98, 0xfffe0000, v98
	v_add3_u32 v99, v104, v99, s86
	v_and_b32_e32 v99, 0xfffe0000, v99
	v_cvt_pk_bf16_f32 v98, v98, v99
	ds_write_b32 v110, v98 offset:3352
	v_bfe_u32 v98, v101, 17, 1
	v_add3_u32 v98, v101, v98, s86
	v_bfe_u32 v99, v105, 17, 1
	v_and_b32_e32 v98, 0xfffe0000, v98
	v_add3_u32 v99, v105, v99, s86
	v_and_b32_e32 v99, 0xfffe0000, v99
	v_cvt_pk_bf16_f32 v98, v98, v99
	ds_write_b32 v110, v98 offset:3480
	s_waitcnt vmcnt(23)
	v_bfe_u32 v98, v90, 17, 1
	v_add3_u32 v90, v90, v98, s86
	s_waitcnt vmcnt(22)
	v_bfe_u32 v98, v94, 17, 1
	v_and_b32_e32 v90, 0xfffe0000, v90
	v_add3_u32 v94, v94, v98, s86
	v_and_b32_e32 v94, 0xfffe0000, v94
	v_cvt_pk_bf16_f32 v90, v90, v94
	ds_write_b32 v110, v90 offset:4128
	v_bfe_u32 v90, v91, 17, 1
	v_add3_u32 v90, v91, v90, s86
	v_bfe_u32 v91, v95, 17, 1
	v_and_b32_e32 v90, 0xfffe0000, v90
	v_add3_u32 v91, v95, v91, s86
	v_and_b32_e32 v91, 0xfffe0000, v91
	v_cvt_pk_bf16_f32 v90, v90, v91
	ds_write_b32 v110, v90 offset:4256
	v_bfe_u32 v90, v92, 17, 1
	v_add3_u32 v90, v92, v90, s86
	v_bfe_u32 v91, v96, 17, 1
	v_and_b32_e32 v90, 0xfffe0000, v90
	v_add3_u32 v91, v96, v91, s86
	v_and_b32_e32 v91, 0xfffe0000, v91
	v_cvt_pk_bf16_f32 v90, v90, v91
	ds_write_b32 v110, v90 offset:4384
	v_bfe_u32 v90, v93, 17, 1
	v_add3_u32 v90, v93, v90, s86
	v_bfe_u32 v91, v97, 17, 1
	v_and_b32_e32 v90, 0xfffe0000, v90
	v_add3_u32 v91, v97, v91, s86
	v_and_b32_e32 v91, 0xfffe0000, v91
	v_cvt_pk_bf16_f32 v90, v90, v91
	ds_write_b32 v110, v90 offset:4512
	s_waitcnt vmcnt(21)
	v_bfe_u32 v90, v82, 17, 1
	v_add3_u32 v82, v82, v90, s86
	s_waitcnt vmcnt(20)
	v_bfe_u32 v90, v86, 17, 1
	v_and_b32_e32 v82, 0xfffe0000, v82
	v_add3_u32 v86, v86, v90, s86
	v_and_b32_e32 v86, 0xfffe0000, v86
	v_cvt_pk_bf16_f32 v82, v82, v86
	ds_write_b32 v110, v82 offset:5160
	v_bfe_u32 v82, v83, 17, 1
	v_add3_u32 v82, v83, v82, s86
	v_bfe_u32 v83, v87, 17, 1
	v_and_b32_e32 v82, 0xfffe0000, v82
	v_add3_u32 v83, v87, v83, s86
	v_and_b32_e32 v83, 0xfffe0000, v83
	v_cvt_pk_bf16_f32 v82, v82, v83
	ds_write_b32 v110, v82 offset:5288
	v_bfe_u32 v82, v84, 17, 1
	v_add3_u32 v82, v84, v82, s86
	v_bfe_u32 v83, v88, 17, 1
	v_and_b32_e32 v82, 0xfffe0000, v82
	v_add3_u32 v83, v88, v83, s86
	v_and_b32_e32 v83, 0xfffe0000, v83
	v_cvt_pk_bf16_f32 v82, v82, v83
	ds_write_b32 v110, v82 offset:5416
	v_bfe_u32 v82, v85, 17, 1
	v_add3_u32 v82, v85, v82, s86
	v_bfe_u32 v83, v89, 17, 1
	v_and_b32_e32 v82, 0xfffe0000, v82
	v_add3_u32 v83, v89, v83, s86
	v_and_b32_e32 v83, 0xfffe0000, v83
	v_cvt_pk_bf16_f32 v82, v82, v83
	ds_write_b32 v110, v82 offset:5544
	s_waitcnt vmcnt(19)
	v_bfe_u32 v82, v74, 17, 1
	v_add3_u32 v74, v74, v82, s86
	s_waitcnt vmcnt(18)
	v_bfe_u32 v82, v78, 17, 1
	v_and_b32_e32 v74, 0xfffe0000, v74
	v_add3_u32 v78, v78, v82, s86
	v_and_b32_e32 v78, 0xfffe0000, v78
	v_cvt_pk_bf16_f32 v74, v74, v78
	ds_write_b32 v110, v74 offset:6192
	v_bfe_u32 v74, v75, 17, 1
	v_add3_u32 v74, v75, v74, s86
	v_bfe_u32 v75, v79, 17, 1
	v_and_b32_e32 v74, 0xfffe0000, v74
	v_add3_u32 v75, v79, v75, s86
	v_and_b32_e32 v75, 0xfffe0000, v75
	v_cvt_pk_bf16_f32 v74, v74, v75
	ds_write_b32 v110, v74 offset:6320
	v_bfe_u32 v74, v76, 17, 1
	v_add3_u32 v74, v76, v74, s86
	v_bfe_u32 v75, v80, 17, 1
	v_and_b32_e32 v74, 0xfffe0000, v74
	v_add3_u32 v75, v80, v75, s86
	v_and_b32_e32 v75, 0xfffe0000, v75
	v_cvt_pk_bf16_f32 v74, v74, v75
	ds_write_b32 v110, v74 offset:6448
	v_bfe_u32 v74, v77, 17, 1
	v_add3_u32 v74, v77, v74, s86
	v_bfe_u32 v75, v81, 17, 1
	v_and_b32_e32 v74, 0xfffe0000, v74
	v_add3_u32 v75, v81, v75, s86
	v_and_b32_e32 v75, 0xfffe0000, v75
	v_cvt_pk_bf16_f32 v74, v74, v75
	ds_write_b32 v110, v74 offset:6576
	s_waitcnt vmcnt(17)
	v_bfe_u32 v74, v66, 17, 1
	v_add3_u32 v66, v66, v74, s86
	s_waitcnt vmcnt(16)
	v_bfe_u32 v74, v70, 17, 1
	v_and_b32_e32 v66, 0xfffe0000, v66
	v_add3_u32 v70, v70, v74, s86
	v_and_b32_e32 v70, 0xfffe0000, v70
	v_cvt_pk_bf16_f32 v66, v66, v70
	ds_write_b32 v110, v66 offset:7224
	v_bfe_u32 v66, v67, 17, 1
	v_add3_u32 v66, v67, v66, s86
	v_bfe_u32 v67, v71, 17, 1
	v_and_b32_e32 v66, 0xfffe0000, v66
	v_add3_u32 v67, v71, v67, s86
	v_and_b32_e32 v67, 0xfffe0000, v67
	v_cvt_pk_bf16_f32 v66, v66, v67
	ds_write_b32 v110, v66 offset:7352
	v_bfe_u32 v66, v68, 17, 1
	v_add3_u32 v66, v68, v66, s86
	v_bfe_u32 v67, v72, 17, 1
	v_and_b32_e32 v66, 0xfffe0000, v66
	v_add3_u32 v67, v72, v67, s86
	v_and_b32_e32 v67, 0xfffe0000, v67
	v_cvt_pk_bf16_f32 v66, v66, v67
	ds_write_b32 v110, v66 offset:7480
	v_bfe_u32 v66, v69, 17, 1
	v_add3_u32 v66, v69, v66, s86
	v_bfe_u32 v67, v73, 17, 1
	v_and_b32_e32 v66, 0xfffe0000, v66
	v_add3_u32 v67, v73, v67, s86
	v_and_b32_e32 v67, 0xfffe0000, v67
	v_cvt_pk_bf16_f32 v66, v66, v67
	ds_write_b32 v110, v66 offset:7608
	s_waitcnt vmcnt(15)
	v_bfe_u32 v66, v58, 17, 1
	v_add3_u32 v58, v58, v66, s86
	s_waitcnt vmcnt(14)
	v_bfe_u32 v66, v62, 17, 1
	v_and_b32_e32 v58, 0xfffe0000, v58
	v_add3_u32 v62, v62, v66, s86
	v_and_b32_e32 v62, 0xfffe0000, v62
	v_cvt_pk_bf16_f32 v58, v58, v62
	ds_write_b32 v110, v58 offset:8256
	v_bfe_u32 v58, v59, 17, 1
	v_add3_u32 v58, v59, v58, s86
	v_bfe_u32 v59, v63, 17, 1
	v_and_b32_e32 v58, 0xfffe0000, v58
	v_add3_u32 v59, v63, v59, s86
	v_and_b32_e32 v59, 0xfffe0000, v59
	v_cvt_pk_bf16_f32 v58, v58, v59
	ds_write_b32 v110, v58 offset:8384
	v_bfe_u32 v58, v60, 17, 1
	v_add3_u32 v58, v60, v58, s86
	v_bfe_u32 v59, v64, 17, 1
	v_and_b32_e32 v58, 0xfffe0000, v58
	v_add3_u32 v59, v64, v59, s86
	v_and_b32_e32 v59, 0xfffe0000, v59
	v_cvt_pk_bf16_f32 v58, v58, v59
	ds_write_b32 v110, v58 offset:8512
	v_bfe_u32 v58, v61, 17, 1
	v_add3_u32 v58, v61, v58, s86
	v_bfe_u32 v59, v65, 17, 1
	v_and_b32_e32 v58, 0xfffe0000, v58
	v_add3_u32 v59, v65, v59, s86
	v_and_b32_e32 v59, 0xfffe0000, v59
	v_cvt_pk_bf16_f32 v58, v58, v59
	ds_write_b32 v110, v58 offset:8640
	s_waitcnt vmcnt(13)
	v_bfe_u32 v58, v50, 17, 1
	v_add3_u32 v50, v50, v58, s86
	s_waitcnt vmcnt(12)
	v_bfe_u32 v58, v54, 17, 1
	v_and_b32_e32 v50, 0xfffe0000, v50
	v_add3_u32 v54, v54, v58, s86
	v_and_b32_e32 v54, 0xfffe0000, v54
	v_cvt_pk_bf16_f32 v50, v50, v54
	ds_write_b32 v110, v50 offset:9288
	v_bfe_u32 v50, v51, 17, 1
	v_add3_u32 v50, v51, v50, s86
	v_bfe_u32 v51, v55, 17, 1
	v_and_b32_e32 v50, 0xfffe0000, v50
	v_add3_u32 v51, v55, v51, s86
	v_and_b32_e32 v51, 0xfffe0000, v51
	v_cvt_pk_bf16_f32 v50, v50, v51
	ds_write_b32 v110, v50 offset:9416
	v_bfe_u32 v50, v52, 17, 1
	v_add3_u32 v50, v52, v50, s86
	v_bfe_u32 v51, v56, 17, 1
	v_and_b32_e32 v50, 0xfffe0000, v50
	v_add3_u32 v51, v56, v51, s86
	v_and_b32_e32 v51, 0xfffe0000, v51
	v_cvt_pk_bf16_f32 v50, v50, v51
	ds_write_b32 v110, v50 offset:9544
	v_bfe_u32 v50, v53, 17, 1
	v_add3_u32 v50, v53, v50, s86
	v_bfe_u32 v51, v57, 17, 1
	v_and_b32_e32 v50, 0xfffe0000, v50
	v_add3_u32 v51, v57, v51, s86
	v_and_b32_e32 v51, 0xfffe0000, v51
	v_cvt_pk_bf16_f32 v50, v50, v51
	ds_write_b32 v110, v50 offset:9672
	s_waitcnt vmcnt(11)
	v_bfe_u32 v50, v42, 17, 1
	v_add3_u32 v42, v42, v50, s86
	s_waitcnt vmcnt(10)
	v_bfe_u32 v50, v46, 17, 1
	v_and_b32_e32 v42, 0xfffe0000, v42
	v_add3_u32 v46, v46, v50, s86
	v_and_b32_e32 v46, 0xfffe0000, v46
	v_cvt_pk_bf16_f32 v42, v42, v46
	ds_write_b32 v110, v42 offset:10320
	v_bfe_u32 v42, v43, 17, 1
	v_add3_u32 v42, v43, v42, s86
	v_bfe_u32 v43, v47, 17, 1
	v_and_b32_e32 v42, 0xfffe0000, v42
	v_add3_u32 v43, v47, v43, s86
	v_and_b32_e32 v43, 0xfffe0000, v43
	v_cvt_pk_bf16_f32 v42, v42, v43
	ds_write_b32 v110, v42 offset:10448
	v_bfe_u32 v42, v44, 17, 1
	v_add3_u32 v42, v44, v42, s86
	v_bfe_u32 v43, v48, 17, 1
	v_and_b32_e32 v42, 0xfffe0000, v42
	v_add3_u32 v43, v48, v43, s86
	v_and_b32_e32 v43, 0xfffe0000, v43
	v_cvt_pk_bf16_f32 v42, v42, v43
	ds_write_b32 v110, v42 offset:10576
	v_bfe_u32 v42, v45, 17, 1
	v_add3_u32 v42, v45, v42, s86
	v_bfe_u32 v43, v49, 17, 1
	v_and_b32_e32 v42, 0xfffe0000, v42
	v_add3_u32 v43, v49, v43, s86
	v_and_b32_e32 v43, 0xfffe0000, v43
	v_cvt_pk_bf16_f32 v42, v42, v43
	ds_write_b32 v110, v42 offset:10704
	s_waitcnt vmcnt(9)
	v_bfe_u32 v42, v34, 17, 1
	v_add3_u32 v34, v34, v42, s86
	s_waitcnt vmcnt(8)
	v_bfe_u32 v42, v38, 17, 1
	v_and_b32_e32 v34, 0xfffe0000, v34
	v_add3_u32 v38, v38, v42, s86
	v_and_b32_e32 v38, 0xfffe0000, v38
	v_cvt_pk_bf16_f32 v34, v34, v38
	ds_write_b32 v110, v34 offset:11352
	v_bfe_u32 v34, v35, 17, 1
	v_add3_u32 v34, v35, v34, s86
	v_bfe_u32 v35, v39, 17, 1
	v_and_b32_e32 v34, 0xfffe0000, v34
	v_add3_u32 v35, v39, v35, s86
	v_and_b32_e32 v35, 0xfffe0000, v35
	v_cvt_pk_bf16_f32 v34, v34, v35
	ds_write_b32 v110, v34 offset:11480
	v_bfe_u32 v34, v36, 17, 1
	v_add3_u32 v34, v36, v34, s86
	v_bfe_u32 v35, v40, 17, 1
	v_and_b32_e32 v34, 0xfffe0000, v34
	v_add3_u32 v35, v40, v35, s86
	v_and_b32_e32 v35, 0xfffe0000, v35
	v_cvt_pk_bf16_f32 v34, v34, v35
	ds_write_b32 v110, v34 offset:11608
	v_bfe_u32 v34, v37, 17, 1
	v_add3_u32 v34, v37, v34, s86
	v_bfe_u32 v35, v41, 17, 1
	v_and_b32_e32 v34, 0xfffe0000, v34
	v_add3_u32 v35, v41, v35, s86
	v_and_b32_e32 v35, 0xfffe0000, v35
	v_cvt_pk_bf16_f32 v34, v34, v35
	ds_write_b32 v110, v34 offset:11736
	s_waitcnt vmcnt(7)
	v_bfe_u32 v34, v26, 17, 1
	v_add3_u32 v26, v26, v34, s86
	s_waitcnt vmcnt(6)
	v_bfe_u32 v34, v30, 17, 1
	v_and_b32_e32 v26, 0xfffe0000, v26
	v_add3_u32 v30, v30, v34, s86
	v_and_b32_e32 v30, 0xfffe0000, v30
	v_cvt_pk_bf16_f32 v26, v26, v30
	ds_write_b32 v110, v26 offset:12384
	v_bfe_u32 v26, v27, 17, 1
	v_add3_u32 v26, v27, v26, s86
	v_bfe_u32 v27, v31, 17, 1
	v_and_b32_e32 v26, 0xfffe0000, v26
	v_add3_u32 v27, v31, v27, s86
	v_and_b32_e32 v27, 0xfffe0000, v27
	v_cvt_pk_bf16_f32 v26, v26, v27
	ds_write_b32 v110, v26 offset:12512
	v_bfe_u32 v26, v28, 17, 1
	v_add3_u32 v26, v28, v26, s86
	v_bfe_u32 v27, v32, 17, 1
	v_and_b32_e32 v26, 0xfffe0000, v26
	v_add3_u32 v27, v32, v27, s86
	v_and_b32_e32 v27, 0xfffe0000, v27
	v_cvt_pk_bf16_f32 v26, v26, v27
	ds_write_b32 v110, v26 offset:12640
	v_bfe_u32 v26, v29, 17, 1
	v_add3_u32 v26, v29, v26, s86
	v_bfe_u32 v27, v33, 17, 1
	v_and_b32_e32 v26, 0xfffe0000, v26
	v_add3_u32 v27, v33, v27, s86
	v_and_b32_e32 v27, 0xfffe0000, v27
	v_cvt_pk_bf16_f32 v26, v26, v27
	ds_write_b32 v110, v26 offset:12768
	s_waitcnt vmcnt(5)
	v_bfe_u32 v26, v18, 17, 1
	v_add3_u32 v18, v18, v26, s86
	s_waitcnt vmcnt(4)
	v_bfe_u32 v26, v22, 17, 1
	v_and_b32_e32 v18, 0xfffe0000, v18
	v_add3_u32 v22, v22, v26, s86
	v_and_b32_e32 v22, 0xfffe0000, v22
	v_cvt_pk_bf16_f32 v18, v18, v22
	ds_write_b32 v110, v18 offset:13416
	v_bfe_u32 v18, v19, 17, 1
	v_add3_u32 v18, v19, v18, s86
	v_bfe_u32 v19, v23, 17, 1
	v_and_b32_e32 v18, 0xfffe0000, v18
	v_add3_u32 v19, v23, v19, s86
	v_and_b32_e32 v19, 0xfffe0000, v19
	v_cvt_pk_bf16_f32 v18, v18, v19
	ds_write_b32 v110, v18 offset:13544
	v_bfe_u32 v18, v20, 17, 1
	v_add3_u32 v18, v20, v18, s86
	v_bfe_u32 v19, v24, 17, 1
	v_and_b32_e32 v18, 0xfffe0000, v18
	v_add3_u32 v19, v24, v19, s86
	v_and_b32_e32 v19, 0xfffe0000, v19
	v_cvt_pk_bf16_f32 v18, v18, v19
	ds_write_b32 v110, v18 offset:13672
	v_bfe_u32 v18, v21, 17, 1
	v_add3_u32 v18, v21, v18, s86
	v_bfe_u32 v19, v25, 17, 1
	v_and_b32_e32 v18, 0xfffe0000, v18
	v_add3_u32 v19, v25, v19, s86
	v_and_b32_e32 v19, 0xfffe0000, v19
	v_cvt_pk_bf16_f32 v18, v18, v19
	ds_write_b32 v110, v18 offset:13800
	s_waitcnt vmcnt(3)
	v_bfe_u32 v18, v10, 17, 1
	v_add3_u32 v10, v10, v18, s86
	s_waitcnt vmcnt(2)
	v_bfe_u32 v18, v14, 17, 1
	v_and_b32_e32 v10, 0xfffe0000, v10
	v_add3_u32 v14, v14, v18, s86
	v_and_b32_e32 v14, 0xfffe0000, v14
	v_cvt_pk_bf16_f32 v10, v10, v14
	ds_write_b32 v110, v10 offset:14448
	v_bfe_u32 v10, v11, 17, 1
	v_add3_u32 v10, v11, v10, s86
	v_bfe_u32 v11, v15, 17, 1
	v_and_b32_e32 v10, 0xfffe0000, v10
	v_add3_u32 v11, v15, v11, s86
	v_and_b32_e32 v11, 0xfffe0000, v11
	v_cvt_pk_bf16_f32 v10, v10, v11
	ds_write_b32 v110, v10 offset:14576
	v_bfe_u32 v10, v12, 17, 1
	v_add3_u32 v10, v12, v10, s86
	v_bfe_u32 v11, v16, 17, 1
	v_and_b32_e32 v10, 0xfffe0000, v10
	v_add3_u32 v11, v16, v11, s86
	v_and_b32_e32 v11, 0xfffe0000, v11
	v_cvt_pk_bf16_f32 v10, v10, v11
	ds_write_b32 v110, v10 offset:14704
	v_bfe_u32 v10, v13, 17, 1
	v_add3_u32 v10, v13, v10, s86
	v_bfe_u32 v11, v17, 17, 1
	v_and_b32_e32 v10, 0xfffe0000, v10
	v_add3_u32 v11, v17, v11, s86
	v_and_b32_e32 v11, 0xfffe0000, v11
	v_cvt_pk_bf16_f32 v10, v10, v11
	ds_write_b32 v110, v10 offset:14832
	s_waitcnt vmcnt(1)
	v_bfe_u32 v10, v2, 17, 1
	v_add3_u32 v2, v2, v10, s86
	s_waitcnt vmcnt(0)
	v_bfe_u32 v10, v6, 17, 1
	v_and_b32_e32 v2, 0xfffe0000, v2
	v_add3_u32 v6, v6, v10, s86
	v_and_b32_e32 v6, 0xfffe0000, v6
	v_cvt_pk_bf16_f32 v2, v2, v6
	ds_write_b32 v110, v2 offset:15480
	v_bfe_u32 v2, v3, 17, 1
	v_add3_u32 v2, v3, v2, s86
	v_bfe_u32 v3, v7, 17, 1
	v_and_b32_e32 v2, 0xfffe0000, v2
	v_add3_u32 v3, v7, v3, s86
	v_and_b32_e32 v3, 0xfffe0000, v3
	v_cvt_pk_bf16_f32 v2, v2, v3
	ds_write_b32 v110, v2 offset:15608
	v_bfe_u32 v2, v4, 17, 1
	v_add3_u32 v2, v4, v2, s86
	v_bfe_u32 v3, v8, 17, 1
	v_and_b32_e32 v2, 0xfffe0000, v2
	v_add3_u32 v3, v8, v3, s86
	v_and_b32_e32 v3, 0xfffe0000, v3
	v_cvt_pk_bf16_f32 v2, v2, v3
	ds_write_b32 v110, v2 offset:15736
	v_bfe_u32 v2, v5, 17, 1
	v_add3_u32 v2, v5, v2, s86
	v_bfe_u32 v3, v9, 17, 1
	v_and_b32_e32 v2, 0xfffe0000, v2
	v_add3_u32 v3, v9, v3, s86
	v_and_b32_e32 v3, 0xfffe0000, v3
	v_cvt_pk_bf16_f32 v2, v2, v3
	ds_write_b32 v110, v2 offset:15864
	s_waitcnt lgkmcnt(0)
	ds_read2_b32 v[20:21], v146 offset1:8
	ds_read2_b32 v[4:5], v146 offset0:129 offset1:137
	v_add_u32_e32 v30, 0x400, v146
	ds_read2_b32 v[22:23], v30 offset0:2 offset1:10
	ds_read2_b32 v[6:7], v30 offset0:131 offset1:139
	v_add_u32_e32 v32, 0x400, v147
	ds_read2_b32 v[24:25], v147 offset1:8
	ds_read2_b32 v[12:13], v147 offset0:129 offset1:137
	ds_read2_b32 v[26:27], v32 offset0:2 offset1:10
	ds_read2_b32 v[14:15], v32 offset0:131 offset1:139
	v_or_b32_e32 v31, s44, v131
	v_lshl_add_u64 v[2:3], s[40:41], 0, v[132:133]
	s_waitcnt lgkmcnt(6)
	v_mov_b32_e32 v9, v4
	v_or3_b32 v4, v31, v145, s2
	v_or_b32_e32 v33, s44, v144
	v_lshl_add_u64 v[2:3], v[2:3], 0, s[4:5]
	v_lshlrev_b32_e32 v132, 7, v4
	v_or3_b32 v4, v33, v145, s2
	v_mov_b32_e32 v8, v20
	s_waitcnt lgkmcnt(5)
	v_mov_b32_e32 v10, v22
	s_waitcnt lgkmcnt(4)
	v_mov_b32_e32 v11, v6
	v_lshl_add_u64 v[16:17], v[2:3], 0, v[132:133]
	v_lshlrev_b32_e32 v132, 7, v4
	global_store_dwordx4 v[16:17], v[8:11], off nt
	v_lshl_add_u64 v[16:17], v[2:3], 0, v[132:133]
	v_add_u32_e32 v4, 0x400, v149
	s_waitcnt lgkmcnt(3)
	v_mov_b32_e32 v8, v24
	s_waitcnt lgkmcnt(2)
	v_mov_b32_e32 v9, v12
	s_waitcnt lgkmcnt(1)
	v_mov_b32_e32 v10, v26
	s_waitcnt lgkmcnt(0)
	v_mov_b32_e32 v11, v14
	global_store_dwordx4 v[16:17], v[8:11], off nt
	ds_read2_b32 v[10:11], v4 offset0:2 offset1:131
	v_or3_b32 v4, v31, v148, s2
	ds_read2_b32 v[8:9], v149 offset1:129
	v_lshlrev_b32_e32 v132, 7, v4
	v_add_u32_e32 v4, 0x400, v150
	ds_read2_b32 v[16:17], v150 offset1:129
	ds_read2_b32 v[18:19], v4 offset0:2 offset1:131
	v_or3_b32 v4, v33, v148, s2
	v_lshl_add_u64 v[28:29], v[2:3], 0, v[132:133]
	v_lshlrev_b32_e32 v132, 7, v4
	s_waitcnt lgkmcnt(2)
	global_store_dwordx4 v[28:29], v[8:11], off nt
	v_mov_b32_e32 v4, v21
	v_mov_b32_e32 v6, v23
	v_lshl_add_u64 v[8:9], v[2:3], 0, v[132:133]
	s_waitcnt lgkmcnt(0)
	global_store_dwordx4 v[8:9], v[16:19], off nt
	v_or3_b32 v8, v31, v151, s2
	v_lshlrev_b32_e32 v132, 7, v8
	v_lshl_add_u64 v[8:9], v[2:3], 0, v[132:133]
	global_store_dwordx4 v[8:9], v[4:7], off nt
	v_mov_b32_e32 v12, v25
	v_mov_b32_e32 v14, v27
	v_or3_b32 v4, v33, v151, s2
	v_add_u32_e32 v6, 0x400, v153
	v_lshlrev_b32_e32 v132, 7, v4
	ds_read2_b32 v[4:5], v153 offset1:129
	ds_read2_b32 v[6:7], v6 offset0:2 offset1:131
	v_lshl_add_u64 v[8:9], v[2:3], 0, v[132:133]
	global_store_dwordx4 v[8:9], v[12:15], off nt
	v_or3_b32 v8, v31, v152, s2
	v_lshlrev_b32_e32 v132, 7, v8
	v_lshl_add_u64 v[8:9], v[2:3], 0, v[132:133]
	s_waitcnt lgkmcnt(0)
	global_store_dwordx4 v[8:9], v[4:7], off nt
	ds_read2_b32 v[4:5], v154 offset1:129
	v_or3_b32 v8, v33, v152, s2
	v_add_u32_e32 v6, 0x400, v154
	ds_read2_b32 v[6:7], v6 offset0:2 offset1:131
	v_lshlrev_b32_e32 v132, 7, v8
	v_lshl_add_u64 v[12:13], v[2:3], 0, v[132:133]
	ds_read2_b32 v[20:21], v146 offset0:16 offset1:24
	ds_read2_b32 v[8:9], v146 offset0:145 offset1:153
	ds_read2_b32 v[22:23], v30 offset0:18 offset1:26
	ds_read2_b32 v[10:11], v30 offset0:147 offset1:155
	s_mov_b64 s[4:5], 0
	s_waitcnt lgkmcnt(4)
	global_store_dwordx4 v[12:13], v[4:7], off nt
	ds_read2_b32 v[24:25], v147 offset0:16 offset1:24
	ds_read2_b32 v[12:13], v147 offset0:145 offset1:153
	ds_read2_b32 v[26:27], v32 offset0:18 offset1:26
	ds_read2_b32 v[14:15], v32 offset0:147 offset1:155
	s_waitcnt lgkmcnt(6)
	v_mov_b32_e32 v5, v8
	v_or3_b32 v8, v31, v155, s2
	v_lshlrev_b32_e32 v132, 7, v8
	v_or3_b32 v8, v33, v155, s2
	v_mov_b32_e32 v4, v20
	s_waitcnt lgkmcnt(5)
	v_mov_b32_e32 v6, v22
	s_waitcnt lgkmcnt(4)
	v_mov_b32_e32 v7, v10
	v_lshl_add_u64 v[16:17], v[2:3], 0, v[132:133]
	v_lshlrev_b32_e32 v132, 7, v8
	global_store_dwordx4 v[16:17], v[4:7], off nt
	v_lshl_add_u64 v[16:17], v[2:3], 0, v[132:133]
	v_or3_b32 v8, v31, v158, s2
	s_waitcnt lgkmcnt(3)
	v_mov_b32_e32 v4, v24
	s_waitcnt lgkmcnt(2)
	v_mov_b32_e32 v5, v12
	s_waitcnt lgkmcnt(1)
	v_mov_b32_e32 v6, v26
	s_waitcnt lgkmcnt(0)
	v_mov_b32_e32 v7, v14
	global_store_dwordx4 v[16:17], v[4:7], off nt
	ds_read2_b32 v[4:5], v159 offset1:129
	v_lshlrev_b32_e32 v132, 7, v8
	v_add_u32_e32 v6, 0x400, v159
	ds_read2_b32 v[6:7], v6 offset0:2 offset1:131
	v_add_u32_e32 v8, 0x400, v160
	ds_read2_b32 v[16:17], v160 offset1:129
	ds_read2_b32 v[18:19], v8 offset0:2 offset1:131
	v_lshl_add_u64 v[28:29], v[2:3], 0, v[132:133]
	s_waitcnt lgkmcnt(2)
	global_store_dwordx4 v[28:29], v[4:7], off nt
	v_mov_b32_e32 v8, v21
	v_mov_b32_e32 v10, v23
	v_or3_b32 v4, v33, v158, s2
	v_lshlrev_b32_e32 v132, 7, v4
	v_lshl_add_u64 v[4:5], v[2:3], 0, v[132:133]
	s_waitcnt lgkmcnt(0)
	global_store_dwordx4 v[4:5], v[16:19], off nt
	v_or3_b32 v4, v31, v161, s2
	v_lshlrev_b32_e32 v132, 7, v4
	v_lshl_add_u64 v[4:5], v[2:3], 0, v[132:133]
	global_store_dwordx4 v[4:5], v[8:11], off nt
	v_or3_b32 v4, v33, v161, s2
	v_lshlrev_b32_e32 v132, 7, v4
	v_mov_b32_e32 v12, v25
	v_mov_b32_e32 v14, v27
	v_lshl_add_u64 v[4:5], v[2:3], 0, v[132:133]
	v_add_u32_e32 v6, 0x400, v163
	global_store_dwordx4 v[4:5], v[12:15], off nt
	ds_read2_b32 v[4:5], v163 offset1:129
	ds_read2_b32 v[6:7], v6 offset0:2 offset1:131
	v_or3_b32 v8, v31, v162, s2
	v_add_u32_e32 v10, 0x400, v164
	v_lshlrev_b32_e32 v132, 7, v8
	ds_read2_b32 v[8:9], v164 offset1:129
	ds_read2_b32 v[10:11], v10 offset0:2 offset1:131
	v_lshl_add_u64 v[12:13], v[2:3], 0, v[132:133]
	s_waitcnt lgkmcnt(2)
	global_store_dwordx4 v[12:13], v[4:7], off nt
	s_nop 1
	v_or3_b32 v4, v33, v162, s2
	v_lshlrev_b32_e32 v132, 7, v4
	v_lshl_add_u64 v[2:3], v[2:3], 0, v[132:133]
	s_waitcnt lgkmcnt(0)
	global_store_dwordx4 v[2:3], v[8:11], off nt
	s_waitcnt lgkmcnt(0)
.LBB0_20:
	s_andn2_b64 vcc, exec, s[4:5]
	s_cbranch_vccnz .LBB0_22
	s_mul_i32 s4, s42, 0x2c00000
	s_mul_hi_i32 s2, s42, 0x2c00000
	s_add_u32 s4, s22, s4
	s_addc_u32 s5, s23, s2
	s_add_i32 s2, s70, 0xe100
	s_bfe_u32 s2, s2, 0xc0004
	v_lshlrev_b32_e32 v2, 2, v135
	v_lshl_or_b32 v132, s2, 19, v2
	v_lshl_add_u64 v[2:3], s[4:5], 0, v[132:133]
	s_lshl_b32 s38, s44, 2
	v_lshl_add_u64 v[2:3], v[2:3], 0, s[38:39]
	v_lshlrev_b32_e32 v132, 2, v130
	v_lshl_add_u64 v[2:3], v[2:3], 0, v[132:133]
	v_add_co_u32_e32 v4, vcc, s68, v2
	s_mov_b32 s4, 0x8000
	s_nop 0
	v_addc_co_u32_e32 v5, vcc, 0, v3, vcc
	global_load_dwordx4 v[106:109], v[2:3], off nt
	global_load_dwordx4 v[110:113], v[4:5], off nt
	v_add_co_u32_e32 v4, vcc, s4, v2
	s_mov_b32 s4, 0xa000
	s_nop 0
	v_addc_co_u32_e32 v5, vcc, 0, v3, vcc
	v_add_co_u32_e32 v6, vcc, s4, v2
	s_mov_b32 s4, 0x10000
	s_nop 0
	v_addc_co_u32_e32 v7, vcc, 0, v3, vcc
	global_load_dwordx4 v[114:117], v[4:5], off nt
	global_load_dwordx4 v[118:121], v[6:7], off nt
	v_add_co_u32_e32 v4, vcc, s4, v2
	s_mov_b32 s4, 0x12000
	s_nop 0
	v_addc_co_u32_e32 v5, vcc, 0, v3, vcc
	v_add_co_u32_e32 v6, vcc, s4, v2
	s_mov_b32 s4, 0x18000
	s_nop 0
	v_addc_co_u32_e32 v7, vcc, 0, v3, vcc
	global_load_dwordx4 v[122:125], v[4:5], off nt
	global_load_dwordx4 v[126:129], v[6:7], off nt
	v_add_co_u32_e32 v4, vcc, s4, v2
	s_mov_b32 s4, 0x1a000
	s_nop 0
	v_addc_co_u32_e32 v5, vcc, 0, v3, vcc
	v_add_co_u32_e32 v6, vcc, s4, v2
	s_mov_b32 s4, 0x20000
	s_nop 0
	v_addc_co_u32_e32 v7, vcc, 0, v3, vcc
	global_load_dwordx4 v[98:101], v[4:5], off nt
	global_load_dwordx4 v[102:105], v[6:7], off nt
	v_add_co_u32_e32 v4, vcc, s4, v2
	s_mov_b32 s4, 0x22000
	s_nop 0
	v_addc_co_u32_e32 v5, vcc, 0, v3, vcc
	v_add_co_u32_e32 v6, vcc, s4, v2
	s_mov_b32 s4, 0x28000
	s_nop 0
	v_addc_co_u32_e32 v7, vcc, 0, v3, vcc
	global_load_dwordx4 v[90:93], v[4:5], off nt
	global_load_dwordx4 v[94:97], v[6:7], off nt
	v_add_co_u32_e32 v4, vcc, s4, v2
	s_mov_b32 s4, 0x30000
	s_nop 0
	v_addc_co_u32_e32 v5, vcc, 0, v3, vcc
	v_add_co_u32_e32 v6, vcc, s58, v2
	s_lshl_b32 s2, s2, 11
	s_nop 0
	v_addc_co_u32_e32 v7, vcc, 0, v3, vcc
	global_load_dwordx4 v[82:85], v[4:5], off nt
	global_load_dwordx4 v[86:89], v[6:7], off nt
	v_add_co_u32_e32 v4, vcc, s4, v2
	s_mov_b32 s4, 0x32000
	s_nop 0
	v_addc_co_u32_e32 v5, vcc, 0, v3, vcc
	v_add_co_u32_e32 v6, vcc, s4, v2
	s_mov_b32 s4, 0x3a000
	s_nop 0
	v_addc_co_u32_e32 v7, vcc, 0, v3, vcc
	global_load_dwordx4 v[74:77], v[4:5], off nt
	global_load_dwordx4 v[78:81], v[6:7], off nt
	v_add_co_u32_e32 v4, vcc, s61, v2
	s_waitcnt vmcnt(13)
	v_bfe_u32 v132, v106, 17, 1
	v_addc_co_u32_e32 v5, vcc, 0, v3, vcc
	v_add_co_u32_e32 v6, vcc, s4, v2
	s_mov_b32 s4, 0x40000
	s_nop 0
	v_addc_co_u32_e32 v7, vcc, 0, v3, vcc
	global_load_dwordx4 v[66:69], v[4:5], off nt
	global_load_dwordx4 v[70:73], v[6:7], off nt
	v_add_co_u32_e32 v4, vcc, s4, v2
	s_mov_b32 s4, 0x42000
	s_nop 0
	v_addc_co_u32_e32 v5, vcc, 0, v3, vcc
	v_add_co_u32_e32 v6, vcc, s4, v2
	s_mov_b32 s4, 0x48000
	s_nop 0
	v_addc_co_u32_e32 v7, vcc, 0, v3, vcc
	global_load_dwordx4 v[58:61], v[4:5], off nt
	global_load_dwordx4 v[62:65], v[6:7], off nt
	v_add_co_u32_e32 v4, vcc, s4, v2
	s_mov_b32 s4, 0x4a000
	s_nop 0
	v_addc_co_u32_e32 v5, vcc, 0, v3, vcc
	v_add_co_u32_e32 v6, vcc, s4, v2
	s_mov_b32 s4, 0x50000
	s_nop 0
	v_addc_co_u32_e32 v7, vcc, 0, v3, vcc
	global_load_dwordx4 v[50:53], v[4:5], off nt
	global_load_dwordx4 v[54:57], v[6:7], off nt
	v_add_co_u32_e32 v4, vcc, s4, v2
	v_add3_u32 v106, v106, v132, s86
	s_nop 0
	v_addc_co_u32_e32 v5, vcc, 0, v3, vcc
	v_add_co_u32_e32 v6, vcc, s75, v2
	s_waitcnt vmcnt(18)
	v_bfe_u32 v132, v110, 17, 1
	v_addc_co_u32_e32 v7, vcc, 0, v3, vcc
	global_load_dwordx4 v[42:45], v[4:5], off nt
	global_load_dwordx4 v[46:49], v[6:7], off nt
	v_add_co_u32_e32 v4, vcc, s76, v2
	v_add3_u32 v110, v110, v132, s86
	s_nop 0
	v_addc_co_u32_e32 v5, vcc, 0, v3, vcc
	v_add_co_u32_e32 v6, vcc, s77, v2
	v_and_b32_e32 v106, 0xfffe0000, v106
	s_nop 0
	v_addc_co_u32_e32 v7, vcc, 0, v3, vcc
	global_load_dwordx4 v[34:37], v[4:5], off nt
	global_load_dwordx4 v[38:41], v[6:7], off nt
	v_add_co_u32_e32 v4, vcc, s78, v2
	v_and_b32_e32 v110, 0xfffe0000, v110
	s_nop 0
	v_addc_co_u32_e32 v5, vcc, 0, v3, vcc
	v_add_co_u32_e32 v6, vcc, s79, v2
	v_lshlrev_b32_e32 v132, 1, v134
	s_nop 0
	v_addc_co_u32_e32 v7, vcc, 0, v3, vcc
	global_load_dwordx4 v[26:29], v[4:5], off nt
	global_load_dwordx4 v[30:33], v[6:7], off nt
	v_add_co_u32_e32 v4, vcc, s80, v2
	s_mov_b64 s[4:5], 0x8400000
	s_nop 0
	v_addc_co_u32_e32 v5, vcc, 0, v3, vcc
	v_add_co_u32_e32 v6, vcc, s81, v2
	s_nop 1
	v_addc_co_u32_e32 v7, vcc, 0, v3, vcc
	global_load_dwordx4 v[18:21], v[4:5], off nt
	global_load_dwordx4 v[22:25], v[6:7], off nt
	v_add_co_u32_e32 v4, vcc, s82, v2
	s_nop 1
	v_addc_co_u32_e32 v5, vcc, 0, v3, vcc
	v_add_co_u32_e32 v6, vcc, s83, v2
	s_nop 1
	v_addc_co_u32_e32 v7, vcc, 0, v3, vcc
	global_load_dwordx4 v[10:13], v[4:5], off nt
	global_load_dwordx4 v[14:17], v[6:7], off nt
	v_add_co_u32_e32 v4, vcc, s84, v2
	s_nop 1
	v_addc_co_u32_e32 v5, vcc, 0, v3, vcc
	v_add_co_u32_e32 v6, vcc, s85, v2
	s_nop 1
	v_addc_co_u32_e32 v7, vcc, 0, v3, vcc
	global_load_dwordx4 v[2:5], v[4:5], off nt
	s_nop 0
	global_load_dwordx4 v[6:9], v[6:7], off nt
	v_cvt_pk_bf16_f32 v106, v106, v110
	v_add_u32_e32 v110, v142, v143
	ds_write_b32 v110, v106
	v_bfe_u32 v106, v107, 17, 1
	v_add3_u32 v106, v107, v106, s86
	v_bfe_u32 v107, v111, 17, 1
	v_and_b32_e32 v106, 0xfffe0000, v106
	v_add3_u32 v107, v111, v107, s86
	v_and_b32_e32 v107, 0xfffe0000, v107
	v_cvt_pk_bf16_f32 v106, v106, v107
	ds_write_b32 v110, v106 offset:128
	v_bfe_u32 v106, v108, 17, 1
	v_add3_u32 v106, v108, v106, s86
	v_bfe_u32 v107, v112, 17, 1
	v_and_b32_e32 v106, 0xfffe0000, v106
	v_add3_u32 v107, v112, v107, s86
	v_and_b32_e32 v107, 0xfffe0000, v107
	v_cvt_pk_bf16_f32 v106, v106, v107
	ds_write_b32 v110, v106 offset:256
	v_bfe_u32 v106, v109, 17, 1
	v_add3_u32 v106, v109, v106, s86
	v_bfe_u32 v107, v113, 17, 1
	v_and_b32_e32 v106, 0xfffe0000, v106
	v_add3_u32 v107, v113, v107, s86
	v_and_b32_e32 v107, 0xfffe0000, v107
	v_cvt_pk_bf16_f32 v106, v106, v107
	ds_write_b32 v110, v106 offset:384
	s_waitcnt vmcnt(29)
	v_bfe_u32 v106, v114, 17, 1
	v_add3_u32 v106, v114, v106, s86
	s_waitcnt vmcnt(28)
	v_bfe_u32 v107, v118, 17, 1
	v_and_b32_e32 v106, 0xfffe0000, v106
	v_add3_u32 v107, v118, v107, s86
	v_and_b32_e32 v107, 0xfffe0000, v107
	v_cvt_pk_bf16_f32 v106, v106, v107
	ds_write_b32 v110, v106 offset:1032
	v_bfe_u32 v106, v115, 17, 1
	v_add3_u32 v106, v115, v106, s86
	v_bfe_u32 v107, v119, 17, 1
	v_and_b32_e32 v106, 0xfffe0000, v106
	v_add3_u32 v107, v119, v107, s86
	v_and_b32_e32 v107, 0xfffe0000, v107
	v_cvt_pk_bf16_f32 v106, v106, v107
	ds_write_b32 v110, v106 offset:1160
	v_bfe_u32 v106, v116, 17, 1
	v_add3_u32 v106, v116, v106, s86
	v_bfe_u32 v107, v120, 17, 1
	v_and_b32_e32 v106, 0xfffe0000, v106
	v_add3_u32 v107, v120, v107, s86
	v_and_b32_e32 v107, 0xfffe0000, v107
	v_cvt_pk_bf16_f32 v106, v106, v107
	ds_write_b32 v110, v106 offset:1288
	v_bfe_u32 v106, v117, 17, 1
	v_add3_u32 v106, v117, v106, s86
	v_bfe_u32 v107, v121, 17, 1
	v_and_b32_e32 v106, 0xfffe0000, v106
	v_add3_u32 v107, v121, v107, s86
	v_and_b32_e32 v107, 0xfffe0000, v107
	v_cvt_pk_bf16_f32 v106, v106, v107
	ds_write_b32 v110, v106 offset:1416
	s_waitcnt vmcnt(27)
	v_bfe_u32 v106, v122, 17, 1
	v_add3_u32 v106, v122, v106, s86
	s_waitcnt vmcnt(26)
	v_bfe_u32 v107, v126, 17, 1
	v_and_b32_e32 v106, 0xfffe0000, v106
	v_add3_u32 v107, v126, v107, s86
	v_and_b32_e32 v107, 0xfffe0000, v107
	v_cvt_pk_bf16_f32 v106, v106, v107
	ds_write_b32 v110, v106 offset:2064
	v_bfe_u32 v106, v123, 17, 1
	v_add3_u32 v106, v123, v106, s86
	v_bfe_u32 v107, v127, 17, 1
	v_and_b32_e32 v106, 0xfffe0000, v106
	v_add3_u32 v107, v127, v107, s86
	v_and_b32_e32 v107, 0xfffe0000, v107
	v_cvt_pk_bf16_f32 v106, v106, v107
	ds_write_b32 v110, v106 offset:2192
	v_bfe_u32 v106, v124, 17, 1
	v_add3_u32 v106, v124, v106, s86
	v_bfe_u32 v107, v128, 17, 1
	v_and_b32_e32 v106, 0xfffe0000, v106
	v_add3_u32 v107, v128, v107, s86
	v_and_b32_e32 v107, 0xfffe0000, v107
	v_cvt_pk_bf16_f32 v106, v106, v107
	ds_write_b32 v110, v106 offset:2320
	v_bfe_u32 v106, v125, 17, 1
	v_add3_u32 v106, v125, v106, s86
	v_bfe_u32 v107, v129, 17, 1
	v_and_b32_e32 v106, 0xfffe0000, v106
	v_add3_u32 v107, v129, v107, s86
	v_and_b32_e32 v107, 0xfffe0000, v107
	v_cvt_pk_bf16_f32 v106, v106, v107
	ds_write_b32 v110, v106 offset:2448
	s_waitcnt vmcnt(25)
	v_bfe_u32 v106, v98, 17, 1
	v_add3_u32 v98, v98, v106, s86
	s_waitcnt vmcnt(24)
	v_bfe_u32 v106, v102, 17, 1
	v_and_b32_e32 v98, 0xfffe0000, v98
	v_add3_u32 v102, v102, v106, s86
	v_and_b32_e32 v102, 0xfffe0000, v102
	v_cvt_pk_bf16_f32 v98, v98, v102
	ds_write_b32 v110, v98 offset:3096
	v_bfe_u32 v98, v99, 17, 1
	v_add3_u32 v98, v99, v98, s86
	v_bfe_u32 v99, v103, 17, 1
	v_and_b32_e32 v98, 0xfffe0000, v98
	v_add3_u32 v99, v103, v99, s86
	v_and_b32_e32 v99, 0xfffe0000, v99
	v_cvt_pk_bf16_f32 v98, v98, v99
	ds_write_b32 v110, v98 offset:3224
	v_bfe_u32 v98, v100, 17, 1
	v_add3_u32 v98, v100, v98, s86
	v_bfe_u32 v99, v104, 17, 1
	v_and_b32_e32 v98, 0xfffe0000, v98
	v_add3_u32 v99, v104, v99, s86
	v_and_b32_e32 v99, 0xfffe0000, v99
	v_cvt_pk_bf16_f32 v98, v98, v99
	ds_write_b32 v110, v98 offset:3352
	v_bfe_u32 v98, v101, 17, 1
	v_add3_u32 v98, v101, v98, s86
	v_bfe_u32 v99, v105, 17, 1
	v_and_b32_e32 v98, 0xfffe0000, v98
	v_add3_u32 v99, v105, v99, s86
	v_and_b32_e32 v99, 0xfffe0000, v99
	v_cvt_pk_bf16_f32 v98, v98, v99
	ds_write_b32 v110, v98 offset:3480
	s_waitcnt vmcnt(23)
	v_bfe_u32 v98, v90, 17, 1
	v_add3_u32 v90, v90, v98, s86
	s_waitcnt vmcnt(22)
	v_bfe_u32 v98, v94, 17, 1
	v_and_b32_e32 v90, 0xfffe0000, v90
	v_add3_u32 v94, v94, v98, s86
	v_and_b32_e32 v94, 0xfffe0000, v94
	v_cvt_pk_bf16_f32 v90, v90, v94
	ds_write_b32 v110, v90 offset:4128
	v_bfe_u32 v90, v91, 17, 1
	v_add3_u32 v90, v91, v90, s86
	v_bfe_u32 v91, v95, 17, 1
	v_and_b32_e32 v90, 0xfffe0000, v90
	v_add3_u32 v91, v95, v91, s86
	v_and_b32_e32 v91, 0xfffe0000, v91
	v_cvt_pk_bf16_f32 v90, v90, v91
	ds_write_b32 v110, v90 offset:4256
	v_bfe_u32 v90, v92, 17, 1
	v_add3_u32 v90, v92, v90, s86
	v_bfe_u32 v91, v96, 17, 1
	v_and_b32_e32 v90, 0xfffe0000, v90
	v_add3_u32 v91, v96, v91, s86
	v_and_b32_e32 v91, 0xfffe0000, v91
	v_cvt_pk_bf16_f32 v90, v90, v91
	ds_write_b32 v110, v90 offset:4384
	v_bfe_u32 v90, v93, 17, 1
	v_add3_u32 v90, v93, v90, s86
	v_bfe_u32 v91, v97, 17, 1
	v_and_b32_e32 v90, 0xfffe0000, v90
	v_add3_u32 v91, v97, v91, s86
	v_and_b32_e32 v91, 0xfffe0000, v91
	v_cvt_pk_bf16_f32 v90, v90, v91
	ds_write_b32 v110, v90 offset:4512
	s_waitcnt vmcnt(21)
	v_bfe_u32 v90, v82, 17, 1
	v_add3_u32 v82, v82, v90, s86
	s_waitcnt vmcnt(20)
	v_bfe_u32 v90, v86, 17, 1
	v_and_b32_e32 v82, 0xfffe0000, v82
	v_add3_u32 v86, v86, v90, s86
	v_and_b32_e32 v86, 0xfffe0000, v86
	v_cvt_pk_bf16_f32 v82, v82, v86
	ds_write_b32 v110, v82 offset:5160
	v_bfe_u32 v82, v83, 17, 1
	v_add3_u32 v82, v83, v82, s86
	v_bfe_u32 v83, v87, 17, 1
	v_and_b32_e32 v82, 0xfffe0000, v82
	v_add3_u32 v83, v87, v83, s86
	v_and_b32_e32 v83, 0xfffe0000, v83
	v_cvt_pk_bf16_f32 v82, v82, v83
	ds_write_b32 v110, v82 offset:5288
	v_bfe_u32 v82, v84, 17, 1
	v_add3_u32 v82, v84, v82, s86
	v_bfe_u32 v83, v88, 17, 1
	v_and_b32_e32 v82, 0xfffe0000, v82
	v_add3_u32 v83, v88, v83, s86
	v_and_b32_e32 v83, 0xfffe0000, v83
	v_cvt_pk_bf16_f32 v82, v82, v83
	ds_write_b32 v110, v82 offset:5416
	v_bfe_u32 v82, v85, 17, 1
	v_add3_u32 v82, v85, v82, s86
	v_bfe_u32 v83, v89, 17, 1
	v_and_b32_e32 v82, 0xfffe0000, v82
	v_add3_u32 v83, v89, v83, s86
	v_and_b32_e32 v83, 0xfffe0000, v83
	v_cvt_pk_bf16_f32 v82, v82, v83
	ds_write_b32 v110, v82 offset:5544
	s_waitcnt vmcnt(19)
	v_bfe_u32 v82, v74, 17, 1
	v_add3_u32 v74, v74, v82, s86
	s_waitcnt vmcnt(18)
	v_bfe_u32 v82, v78, 17, 1
	v_and_b32_e32 v74, 0xfffe0000, v74
	v_add3_u32 v78, v78, v82, s86
	v_and_b32_e32 v78, 0xfffe0000, v78
	v_cvt_pk_bf16_f32 v74, v74, v78
	ds_write_b32 v110, v74 offset:6192
	v_bfe_u32 v74, v75, 17, 1
	v_add3_u32 v74, v75, v74, s86
	v_bfe_u32 v75, v79, 17, 1
	v_and_b32_e32 v74, 0xfffe0000, v74
	v_add3_u32 v75, v79, v75, s86
	v_and_b32_e32 v75, 0xfffe0000, v75
	v_cvt_pk_bf16_f32 v74, v74, v75
	ds_write_b32 v110, v74 offset:6320
	v_bfe_u32 v74, v76, 17, 1
	v_add3_u32 v74, v76, v74, s86
	v_bfe_u32 v75, v80, 17, 1
	v_and_b32_e32 v74, 0xfffe0000, v74
	v_add3_u32 v75, v80, v75, s86
	v_and_b32_e32 v75, 0xfffe0000, v75
	v_cvt_pk_bf16_f32 v74, v74, v75
	ds_write_b32 v110, v74 offset:6448
	v_bfe_u32 v74, v77, 17, 1
	v_add3_u32 v74, v77, v74, s86
	v_bfe_u32 v75, v81, 17, 1
	v_and_b32_e32 v74, 0xfffe0000, v74
	v_add3_u32 v75, v81, v75, s86
	v_and_b32_e32 v75, 0xfffe0000, v75
	v_cvt_pk_bf16_f32 v74, v74, v75
	ds_write_b32 v110, v74 offset:6576
	s_waitcnt vmcnt(17)
	v_bfe_u32 v74, v66, 17, 1
	v_add3_u32 v66, v66, v74, s86
	s_waitcnt vmcnt(16)
	v_bfe_u32 v74, v70, 17, 1
	v_and_b32_e32 v66, 0xfffe0000, v66
	v_add3_u32 v70, v70, v74, s86
	v_and_b32_e32 v70, 0xfffe0000, v70
	v_cvt_pk_bf16_f32 v66, v66, v70
	ds_write_b32 v110, v66 offset:7224
	v_bfe_u32 v66, v67, 17, 1
	v_add3_u32 v66, v67, v66, s86
	v_bfe_u32 v67, v71, 17, 1
	v_and_b32_e32 v66, 0xfffe0000, v66
	v_add3_u32 v67, v71, v67, s86
	v_and_b32_e32 v67, 0xfffe0000, v67
	v_cvt_pk_bf16_f32 v66, v66, v67
	ds_write_b32 v110, v66 offset:7352
	v_bfe_u32 v66, v68, 17, 1
	v_add3_u32 v66, v68, v66, s86
	v_bfe_u32 v67, v72, 17, 1
	v_and_b32_e32 v66, 0xfffe0000, v66
	v_add3_u32 v67, v72, v67, s86
	v_and_b32_e32 v67, 0xfffe0000, v67
	v_cvt_pk_bf16_f32 v66, v66, v67
	ds_write_b32 v110, v66 offset:7480
	v_bfe_u32 v66, v69, 17, 1
	v_add3_u32 v66, v69, v66, s86
	v_bfe_u32 v67, v73, 17, 1
	v_and_b32_e32 v66, 0xfffe0000, v66
	v_add3_u32 v67, v73, v67, s86
	v_and_b32_e32 v67, 0xfffe0000, v67
	v_cvt_pk_bf16_f32 v66, v66, v67
	ds_write_b32 v110, v66 offset:7608
	s_waitcnt vmcnt(15)
	v_bfe_u32 v66, v58, 17, 1
	v_add3_u32 v58, v58, v66, s86
	s_waitcnt vmcnt(14)
	v_bfe_u32 v66, v62, 17, 1
	v_and_b32_e32 v58, 0xfffe0000, v58
	v_add3_u32 v62, v62, v66, s86
	v_and_b32_e32 v62, 0xfffe0000, v62
	v_cvt_pk_bf16_f32 v58, v58, v62
	ds_write_b32 v110, v58 offset:8256
	v_bfe_u32 v58, v59, 17, 1
	v_add3_u32 v58, v59, v58, s86
	v_bfe_u32 v59, v63, 17, 1
	v_and_b32_e32 v58, 0xfffe0000, v58
	v_add3_u32 v59, v63, v59, s86
	v_and_b32_e32 v59, 0xfffe0000, v59
	v_cvt_pk_bf16_f32 v58, v58, v59
	ds_write_b32 v110, v58 offset:8384
	v_bfe_u32 v58, v60, 17, 1
	v_add3_u32 v58, v60, v58, s86
	v_bfe_u32 v59, v64, 17, 1
	v_and_b32_e32 v58, 0xfffe0000, v58
	v_add3_u32 v59, v64, v59, s86
	v_and_b32_e32 v59, 0xfffe0000, v59
	v_cvt_pk_bf16_f32 v58, v58, v59
	ds_write_b32 v110, v58 offset:8512
	v_bfe_u32 v58, v61, 17, 1
	v_add3_u32 v58, v61, v58, s86
	v_bfe_u32 v59, v65, 17, 1
	v_and_b32_e32 v58, 0xfffe0000, v58
	v_add3_u32 v59, v65, v59, s86
	v_and_b32_e32 v59, 0xfffe0000, v59
	v_cvt_pk_bf16_f32 v58, v58, v59
	ds_write_b32 v110, v58 offset:8640
	s_waitcnt vmcnt(13)
	v_bfe_u32 v58, v50, 17, 1
	v_add3_u32 v50, v50, v58, s86
	s_waitcnt vmcnt(12)
	v_bfe_u32 v58, v54, 17, 1
	v_and_b32_e32 v50, 0xfffe0000, v50
	v_add3_u32 v54, v54, v58, s86
	v_and_b32_e32 v54, 0xfffe0000, v54
	v_cvt_pk_bf16_f32 v50, v50, v54
	ds_write_b32 v110, v50 offset:9288
	v_bfe_u32 v50, v51, 17, 1
	v_add3_u32 v50, v51, v50, s86
	v_bfe_u32 v51, v55, 17, 1
	v_and_b32_e32 v50, 0xfffe0000, v50
	v_add3_u32 v51, v55, v51, s86
	v_and_b32_e32 v51, 0xfffe0000, v51
	v_cvt_pk_bf16_f32 v50, v50, v51
	ds_write_b32 v110, v50 offset:9416
	v_bfe_u32 v50, v52, 17, 1
	v_add3_u32 v50, v52, v50, s86
	v_bfe_u32 v51, v56, 17, 1
	v_and_b32_e32 v50, 0xfffe0000, v50
	v_add3_u32 v51, v56, v51, s86
	v_and_b32_e32 v51, 0xfffe0000, v51
	v_cvt_pk_bf16_f32 v50, v50, v51
	ds_write_b32 v110, v50 offset:9544
	v_bfe_u32 v50, v53, 17, 1
	v_add3_u32 v50, v53, v50, s86
	v_bfe_u32 v51, v57, 17, 1
	v_and_b32_e32 v50, 0xfffe0000, v50
	v_add3_u32 v51, v57, v51, s86
	v_and_b32_e32 v51, 0xfffe0000, v51
	v_cvt_pk_bf16_f32 v50, v50, v51
	ds_write_b32 v110, v50 offset:9672
	s_waitcnt vmcnt(11)
	v_bfe_u32 v50, v42, 17, 1
	v_add3_u32 v42, v42, v50, s86
	s_waitcnt vmcnt(10)
	v_bfe_u32 v50, v46, 17, 1
	v_and_b32_e32 v42, 0xfffe0000, v42
	v_add3_u32 v46, v46, v50, s86
	v_and_b32_e32 v46, 0xfffe0000, v46
	v_cvt_pk_bf16_f32 v42, v42, v46
	ds_write_b32 v110, v42 offset:10320
	v_bfe_u32 v42, v43, 17, 1
	v_add3_u32 v42, v43, v42, s86
	v_bfe_u32 v43, v47, 17, 1
	v_and_b32_e32 v42, 0xfffe0000, v42
	v_add3_u32 v43, v47, v43, s86
	v_and_b32_e32 v43, 0xfffe0000, v43
	v_cvt_pk_bf16_f32 v42, v42, v43
	ds_write_b32 v110, v42 offset:10448
	v_bfe_u32 v42, v44, 17, 1
	v_add3_u32 v42, v44, v42, s86
	v_bfe_u32 v43, v48, 17, 1
	v_and_b32_e32 v42, 0xfffe0000, v42
	v_add3_u32 v43, v48, v43, s86
	v_and_b32_e32 v43, 0xfffe0000, v43
	v_cvt_pk_bf16_f32 v42, v42, v43
	ds_write_b32 v110, v42 offset:10576
	v_bfe_u32 v42, v45, 17, 1
	v_add3_u32 v42, v45, v42, s86
	v_bfe_u32 v43, v49, 17, 1
	v_and_b32_e32 v42, 0xfffe0000, v42
	v_add3_u32 v43, v49, v43, s86
	v_and_b32_e32 v43, 0xfffe0000, v43
	v_cvt_pk_bf16_f32 v42, v42, v43
	ds_write_b32 v110, v42 offset:10704
	s_waitcnt vmcnt(9)
	v_bfe_u32 v42, v34, 17, 1
	v_add3_u32 v34, v34, v42, s86
	s_waitcnt vmcnt(8)
	v_bfe_u32 v42, v38, 17, 1
	v_and_b32_e32 v34, 0xfffe0000, v34
	v_add3_u32 v38, v38, v42, s86
	v_and_b32_e32 v38, 0xfffe0000, v38
	v_cvt_pk_bf16_f32 v34, v34, v38
	ds_write_b32 v110, v34 offset:11352
	v_bfe_u32 v34, v35, 17, 1
	v_add3_u32 v34, v35, v34, s86
	v_bfe_u32 v35, v39, 17, 1
	v_and_b32_e32 v34, 0xfffe0000, v34
	v_add3_u32 v35, v39, v35, s86
	v_and_b32_e32 v35, 0xfffe0000, v35
	v_cvt_pk_bf16_f32 v34, v34, v35
	ds_write_b32 v110, v34 offset:11480
	v_bfe_u32 v34, v36, 17, 1
	v_add3_u32 v34, v36, v34, s86
	v_bfe_u32 v35, v40, 17, 1
	v_and_b32_e32 v34, 0xfffe0000, v34
	v_add3_u32 v35, v40, v35, s86
	v_and_b32_e32 v35, 0xfffe0000, v35
	v_cvt_pk_bf16_f32 v34, v34, v35
	ds_write_b32 v110, v34 offset:11608
	v_bfe_u32 v34, v37, 17, 1
	v_add3_u32 v34, v37, v34, s86
	v_bfe_u32 v35, v41, 17, 1
	v_and_b32_e32 v34, 0xfffe0000, v34
	v_add3_u32 v35, v41, v35, s86
	v_and_b32_e32 v35, 0xfffe0000, v35
	v_cvt_pk_bf16_f32 v34, v34, v35
	ds_write_b32 v110, v34 offset:11736
	s_waitcnt vmcnt(7)
	v_bfe_u32 v34, v26, 17, 1
	v_add3_u32 v26, v26, v34, s86
	s_waitcnt vmcnt(6)
	v_bfe_u32 v34, v30, 17, 1
	v_and_b32_e32 v26, 0xfffe0000, v26
	v_add3_u32 v30, v30, v34, s86
	v_and_b32_e32 v30, 0xfffe0000, v30
	v_cvt_pk_bf16_f32 v26, v26, v30
	ds_write_b32 v110, v26 offset:12384
	v_bfe_u32 v26, v27, 17, 1
	v_add3_u32 v26, v27, v26, s86
	v_bfe_u32 v27, v31, 17, 1
	v_and_b32_e32 v26, 0xfffe0000, v26
	v_add3_u32 v27, v31, v27, s86
	v_and_b32_e32 v27, 0xfffe0000, v27
	v_cvt_pk_bf16_f32 v26, v26, v27
	ds_write_b32 v110, v26 offset:12512
	v_bfe_u32 v26, v28, 17, 1
	v_add3_u32 v26, v28, v26, s86
	v_bfe_u32 v27, v32, 17, 1
	v_and_b32_e32 v26, 0xfffe0000, v26
	v_add3_u32 v27, v32, v27, s86
	v_and_b32_e32 v27, 0xfffe0000, v27
	v_cvt_pk_bf16_f32 v26, v26, v27
	ds_write_b32 v110, v26 offset:12640
	v_bfe_u32 v26, v29, 17, 1
	v_add3_u32 v26, v29, v26, s86
	v_bfe_u32 v27, v33, 17, 1
	v_and_b32_e32 v26, 0xfffe0000, v26
	v_add3_u32 v27, v33, v27, s86
	v_and_b32_e32 v27, 0xfffe0000, v27
	v_cvt_pk_bf16_f32 v26, v26, v27
	ds_write_b32 v110, v26 offset:12768
	s_waitcnt vmcnt(5)
	v_bfe_u32 v26, v18, 17, 1
	v_add3_u32 v18, v18, v26, s86
	s_waitcnt vmcnt(4)
	v_bfe_u32 v26, v22, 17, 1
	v_and_b32_e32 v18, 0xfffe0000, v18
	v_add3_u32 v22, v22, v26, s86
	v_and_b32_e32 v22, 0xfffe0000, v22
	v_cvt_pk_bf16_f32 v18, v18, v22
	ds_write_b32 v110, v18 offset:13416
	v_bfe_u32 v18, v19, 17, 1
	v_add3_u32 v18, v19, v18, s86
	v_bfe_u32 v19, v23, 17, 1
	v_and_b32_e32 v18, 0xfffe0000, v18
	v_add3_u32 v19, v23, v19, s86
	v_and_b32_e32 v19, 0xfffe0000, v19
	v_cvt_pk_bf16_f32 v18, v18, v19
	ds_write_b32 v110, v18 offset:13544
	v_bfe_u32 v18, v20, 17, 1
	v_add3_u32 v18, v20, v18, s86
	v_bfe_u32 v19, v24, 17, 1
	v_and_b32_e32 v18, 0xfffe0000, v18
	v_add3_u32 v19, v24, v19, s86
	v_and_b32_e32 v19, 0xfffe0000, v19
	v_cvt_pk_bf16_f32 v18, v18, v19
	ds_write_b32 v110, v18 offset:13672
	v_bfe_u32 v18, v21, 17, 1
	v_add3_u32 v18, v21, v18, s86
	v_bfe_u32 v19, v25, 17, 1
	v_and_b32_e32 v18, 0xfffe0000, v18
	v_add3_u32 v19, v25, v19, s86
	v_and_b32_e32 v19, 0xfffe0000, v19
	v_cvt_pk_bf16_f32 v18, v18, v19
	ds_write_b32 v110, v18 offset:13800
	s_waitcnt vmcnt(3)
	v_bfe_u32 v18, v10, 17, 1
	v_add3_u32 v10, v10, v18, s86
	s_waitcnt vmcnt(2)
	v_bfe_u32 v18, v14, 17, 1
	v_and_b32_e32 v10, 0xfffe0000, v10
	v_add3_u32 v14, v14, v18, s86
	v_and_b32_e32 v14, 0xfffe0000, v14
	v_cvt_pk_bf16_f32 v10, v10, v14
	ds_write_b32 v110, v10 offset:14448
	v_bfe_u32 v10, v11, 17, 1
	v_add3_u32 v10, v11, v10, s86
	v_bfe_u32 v11, v15, 17, 1
	v_and_b32_e32 v10, 0xfffe0000, v10
	v_add3_u32 v11, v15, v11, s86
	v_and_b32_e32 v11, 0xfffe0000, v11
	v_cvt_pk_bf16_f32 v10, v10, v11
	ds_write_b32 v110, v10 offset:14576
	v_bfe_u32 v10, v12, 17, 1
	v_add3_u32 v10, v12, v10, s86
	v_bfe_u32 v11, v16, 17, 1
	v_and_b32_e32 v10, 0xfffe0000, v10
	v_add3_u32 v11, v16, v11, s86
	v_and_b32_e32 v11, 0xfffe0000, v11
	v_cvt_pk_bf16_f32 v10, v10, v11
	ds_write_b32 v110, v10 offset:14704
	v_bfe_u32 v10, v13, 17, 1
	v_add3_u32 v10, v13, v10, s86
	v_bfe_u32 v11, v17, 17, 1
	v_and_b32_e32 v10, 0xfffe0000, v10
	v_add3_u32 v11, v17, v11, s86
	v_and_b32_e32 v11, 0xfffe0000, v11
	v_cvt_pk_bf16_f32 v10, v10, v11
	ds_write_b32 v110, v10 offset:14832
	s_waitcnt vmcnt(1)
	v_bfe_u32 v10, v2, 17, 1
	v_add3_u32 v2, v2, v10, s86
	s_waitcnt vmcnt(0)
	v_bfe_u32 v10, v6, 17, 1
	v_and_b32_e32 v2, 0xfffe0000, v2
	v_add3_u32 v6, v6, v10, s86
	v_and_b32_e32 v6, 0xfffe0000, v6
	v_cvt_pk_bf16_f32 v2, v2, v6
	ds_write_b32 v110, v2 offset:15480
	v_bfe_u32 v2, v3, 17, 1
	v_add3_u32 v2, v3, v2, s86
	v_bfe_u32 v3, v7, 17, 1
	v_and_b32_e32 v2, 0xfffe0000, v2
	v_add3_u32 v3, v7, v3, s86
	v_and_b32_e32 v3, 0xfffe0000, v3
	v_cvt_pk_bf16_f32 v2, v2, v3
	ds_write_b32 v110, v2 offset:15608
	v_bfe_u32 v2, v4, 17, 1
	v_add3_u32 v2, v4, v2, s86
	v_bfe_u32 v3, v8, 17, 1
	v_and_b32_e32 v2, 0xfffe0000, v2
	v_add3_u32 v3, v8, v3, s86
	v_and_b32_e32 v3, 0xfffe0000, v3
	v_cvt_pk_bf16_f32 v2, v2, v3
	ds_write_b32 v110, v2 offset:15736
	v_bfe_u32 v2, v5, 17, 1
	v_add3_u32 v2, v5, v2, s86
	v_bfe_u32 v3, v9, 17, 1
	v_and_b32_e32 v2, 0xfffe0000, v2
	v_add3_u32 v3, v9, v3, s86
	v_and_b32_e32 v3, 0xfffe0000, v3
	v_cvt_pk_bf16_f32 v2, v2, v3
	ds_write_b32 v110, v2 offset:15864
	s_waitcnt lgkmcnt(0)
	ds_read2_b32 v[20:21], v146 offset1:8
	ds_read2_b32 v[4:5], v146 offset0:129 offset1:137
	v_add_u32_e32 v30, 0x400, v146
	ds_read2_b32 v[22:23], v30 offset0:2 offset1:10
	ds_read2_b32 v[6:7], v30 offset0:131 offset1:139
	v_add_u32_e32 v32, 0x400, v147
	ds_read2_b32 v[24:25], v147 offset1:8
	ds_read2_b32 v[12:13], v147 offset0:129 offset1:137
	ds_read2_b32 v[26:27], v32 offset0:2 offset1:10
	ds_read2_b32 v[14:15], v32 offset0:131 offset1:139
	v_or_b32_e32 v31, s44, v131
	v_lshl_add_u64 v[2:3], s[40:41], 0, v[132:133]
	s_waitcnt lgkmcnt(6)
	v_mov_b32_e32 v9, v4
	v_or3_b32 v4, v31, v145, s2
	v_or_b32_e32 v33, s44, v144
	v_lshl_add_u64 v[2:3], v[2:3], 0, s[4:5]
	v_lshlrev_b32_e32 v132, 7, v4
	v_or3_b32 v4, v33, v145, s2
	v_mov_b32_e32 v8, v20
	s_waitcnt lgkmcnt(5)
	v_mov_b32_e32 v10, v22
	s_waitcnt lgkmcnt(4)
	v_mov_b32_e32 v11, v6
	v_lshl_add_u64 v[16:17], v[2:3], 0, v[132:133]
	v_lshlrev_b32_e32 v132, 7, v4
	global_store_dwordx4 v[16:17], v[8:11], off nt
	v_lshl_add_u64 v[16:17], v[2:3], 0, v[132:133]
	v_add_u32_e32 v4, 0x400, v149
	s_waitcnt lgkmcnt(3)
	v_mov_b32_e32 v8, v24
	s_waitcnt lgkmcnt(2)
	v_mov_b32_e32 v9, v12
	s_waitcnt lgkmcnt(1)
	v_mov_b32_e32 v10, v26
	s_waitcnt lgkmcnt(0)
	v_mov_b32_e32 v11, v14
	global_store_dwordx4 v[16:17], v[8:11], off nt
	ds_read2_b32 v[10:11], v4 offset0:2 offset1:131
	v_or3_b32 v4, v31, v148, s2
	ds_read2_b32 v[8:9], v149 offset1:129
	v_lshlrev_b32_e32 v132, 7, v4
	v_add_u32_e32 v4, 0x400, v150
	ds_read2_b32 v[16:17], v150 offset1:129
	ds_read2_b32 v[18:19], v4 offset0:2 offset1:131
	v_or3_b32 v4, v33, v148, s2
	v_lshl_add_u64 v[28:29], v[2:3], 0, v[132:133]
	v_lshlrev_b32_e32 v132, 7, v4
	s_waitcnt lgkmcnt(2)
	global_store_dwordx4 v[28:29], v[8:11], off nt
	v_mov_b32_e32 v4, v21
	v_mov_b32_e32 v6, v23
	v_lshl_add_u64 v[8:9], v[2:3], 0, v[132:133]
	s_waitcnt lgkmcnt(0)
	global_store_dwordx4 v[8:9], v[16:19], off nt
	v_or3_b32 v8, v31, v151, s2
	v_lshlrev_b32_e32 v132, 7, v8
	v_lshl_add_u64 v[8:9], v[2:3], 0, v[132:133]
	global_store_dwordx4 v[8:9], v[4:7], off nt
	v_mov_b32_e32 v12, v25
	v_mov_b32_e32 v14, v27
	v_or3_b32 v4, v33, v151, s2
	v_add_u32_e32 v6, 0x400, v153
	v_lshlrev_b32_e32 v132, 7, v4
	ds_read2_b32 v[4:5], v153 offset1:129
	ds_read2_b32 v[6:7], v6 offset0:2 offset1:131
	v_lshl_add_u64 v[8:9], v[2:3], 0, v[132:133]
	global_store_dwordx4 v[8:9], v[12:15], off nt
	v_or3_b32 v8, v31, v152, s2
	v_lshlrev_b32_e32 v132, 7, v8
	v_lshl_add_u64 v[8:9], v[2:3], 0, v[132:133]
	s_waitcnt lgkmcnt(0)
	global_store_dwordx4 v[8:9], v[4:7], off nt
	ds_read2_b32 v[4:5], v154 offset1:129
	v_or3_b32 v8, v33, v152, s2
	v_add_u32_e32 v6, 0x400, v154
	ds_read2_b32 v[6:7], v6 offset0:2 offset1:131
	v_lshlrev_b32_e32 v132, 7, v8
	v_lshl_add_u64 v[12:13], v[2:3], 0, v[132:133]
	ds_read2_b32 v[20:21], v146 offset0:16 offset1:24
	ds_read2_b32 v[8:9], v146 offset0:145 offset1:153
	ds_read2_b32 v[22:23], v30 offset0:18 offset1:26
	ds_read2_b32 v[10:11], v30 offset0:147 offset1:155
	s_waitcnt lgkmcnt(4)
	global_store_dwordx4 v[12:13], v[4:7], off nt
	ds_read2_b32 v[24:25], v147 offset0:16 offset1:24
	ds_read2_b32 v[12:13], v147 offset0:145 offset1:153
	ds_read2_b32 v[26:27], v32 offset0:18 offset1:26
	ds_read2_b32 v[14:15], v32 offset0:147 offset1:155
	s_waitcnt lgkmcnt(6)
	v_mov_b32_e32 v5, v8
	v_or3_b32 v8, v31, v155, s2
	v_lshlrev_b32_e32 v132, 7, v8
	v_or3_b32 v8, v33, v155, s2
	v_mov_b32_e32 v4, v20
	s_waitcnt lgkmcnt(5)
	v_mov_b32_e32 v6, v22
	s_waitcnt lgkmcnt(4)
	v_mov_b32_e32 v7, v10
	v_lshl_add_u64 v[16:17], v[2:3], 0, v[132:133]
	v_lshlrev_b32_e32 v132, 7, v8
	global_store_dwordx4 v[16:17], v[4:7], off nt
	v_lshl_add_u64 v[16:17], v[2:3], 0, v[132:133]
	v_or3_b32 v8, v31, v158, s2
	s_waitcnt lgkmcnt(3)
	v_mov_b32_e32 v4, v24
	s_waitcnt lgkmcnt(2)
	v_mov_b32_e32 v5, v12
	s_waitcnt lgkmcnt(1)
	v_mov_b32_e32 v6, v26
	s_waitcnt lgkmcnt(0)
	v_mov_b32_e32 v7, v14
	global_store_dwordx4 v[16:17], v[4:7], off nt
	ds_read2_b32 v[4:5], v159 offset1:129
	v_lshlrev_b32_e32 v132, 7, v8
	v_add_u32_e32 v6, 0x400, v159
	ds_read2_b32 v[6:7], v6 offset0:2 offset1:131
	v_add_u32_e32 v8, 0x400, v160
	ds_read2_b32 v[16:17], v160 offset1:129
	ds_read2_b32 v[18:19], v8 offset0:2 offset1:131
	v_lshl_add_u64 v[28:29], v[2:3], 0, v[132:133]
	s_waitcnt lgkmcnt(2)
	global_store_dwordx4 v[28:29], v[4:7], off nt
	v_mov_b32_e32 v8, v21
	v_mov_b32_e32 v10, v23
	v_or3_b32 v4, v33, v158, s2
	v_lshlrev_b32_e32 v132, 7, v4
	v_lshl_add_u64 v[4:5], v[2:3], 0, v[132:133]
	s_waitcnt lgkmcnt(0)
	global_store_dwordx4 v[4:5], v[16:19], off nt
	v_or3_b32 v4, v31, v161, s2
	v_lshlrev_b32_e32 v132, 7, v4
	v_lshl_add_u64 v[4:5], v[2:3], 0, v[132:133]
	global_store_dwordx4 v[4:5], v[8:11], off nt
	v_or3_b32 v4, v33, v161, s2
	v_lshlrev_b32_e32 v132, 7, v4
	v_mov_b32_e32 v12, v25
	v_mov_b32_e32 v14, v27
	v_lshl_add_u64 v[4:5], v[2:3], 0, v[132:133]
	v_add_u32_e32 v6, 0x400, v163
	global_store_dwordx4 v[4:5], v[12:15], off nt
	ds_read2_b32 v[4:5], v163 offset1:129
	ds_read2_b32 v[6:7], v6 offset0:2 offset1:131
	v_or3_b32 v8, v31, v162, s2
	v_add_u32_e32 v10, 0x400, v164
	v_lshlrev_b32_e32 v132, 7, v8
	ds_read2_b32 v[8:9], v164 offset1:129
	ds_read2_b32 v[10:11], v10 offset0:2 offset1:131
	v_lshl_add_u64 v[12:13], v[2:3], 0, v[132:133]
	s_waitcnt lgkmcnt(2)
	global_store_dwordx4 v[12:13], v[4:7], off nt
	s_nop 1
	v_or3_b32 v4, v33, v162, s2
	v_lshlrev_b32_e32 v132, 7, v4
	v_lshl_add_u64 v[2:3], v[2:3], 0, v[132:133]
	s_waitcnt lgkmcnt(0)
	global_store_dwordx4 v[2:3], v[8:11], off nt
	s_waitcnt lgkmcnt(0)

.LBB0_23:
	s_andn2_b64 vcc, exec, s[4:5]
	s_cbranch_vccnz .LBB0_25
	s_mul_i32 s4, s42, 0x2c00000
	s_mul_hi_i32 s2, s42, 0x2c00000
	s_add_u32 s44, s24, s4
	s_addc_u32 s45, s25, s2
	s_add_i32 s2, s70, 0xe680
	s_bfe_u32 s4, s2, 0xc0004
	v_lshlrev_b32_e32 v2, 2, v135
	s_and_b32 s2, s46, 0x780
	v_lshl_or_b32 v132, s4, 19, v2
	v_lshl_add_u64 v[2:3], s[44:45], 0, v[132:133]
	s_lshl_b32 s38, s2, 2
	v_lshl_add_u64 v[2:3], v[2:3], 0, s[38:39]
	v_lshlrev_b32_e32 v132, 2, v130
	v_lshl_add_u64 v[2:3], v[2:3], 0, v[132:133]
	v_add_co_u32_e32 v4, vcc, s68, v2
	s_mov_b32 s5, 0x8000
	s_nop 0
	v_addc_co_u32_e32 v5, vcc, 0, v3, vcc
	global_load_dwordx4 v[106:109], v[2:3], off nt
	global_load_dwordx4 v[110:113], v[4:5], off nt
	v_add_co_u32_e32 v4, vcc, s5, v2
	s_mov_b32 s5, 0xa000
	s_nop 0
	v_addc_co_u32_e32 v5, vcc, 0, v3, vcc
	v_add_co_u32_e32 v6, vcc, s5, v2
	s_mov_b32 s5, 0x10000
	s_nop 0
	v_addc_co_u32_e32 v7, vcc, 0, v3, vcc
	global_load_dwordx4 v[114:117], v[4:5], off nt
	global_load_dwordx4 v[118:121], v[6:7], off nt
	v_add_co_u32_e32 v4, vcc, s5, v2
	s_mov_b32 s5, 0x12000
	s_nop 0
	v_addc_co_u32_e32 v5, vcc, 0, v3, vcc
	v_add_co_u32_e32 v6, vcc, s5, v2
	s_mov_b32 s5, 0x18000
	s_nop 0
	v_addc_co_u32_e32 v7, vcc, 0, v3, vcc
	global_load_dwordx4 v[122:125], v[4:5], off nt
	global_load_dwordx4 v[126:129], v[6:7], off nt
	v_add_co_u32_e32 v4, vcc, s5, v2
	s_mov_b32 s5, 0x1a000
	s_nop 0
	v_addc_co_u32_e32 v5, vcc, 0, v3, vcc
	v_add_co_u32_e32 v6, vcc, s5, v2
	s_mov_b32 s5, 0x20000
	s_nop 0
	v_addc_co_u32_e32 v7, vcc, 0, v3, vcc
	global_load_dwordx4 v[98:101], v[4:5], off nt
	global_load_dwordx4 v[102:105], v[6:7], off nt
	v_add_co_u32_e32 v4, vcc, s5, v2
	s_mov_b32 s5, 0x22000
	s_nop 0
	v_addc_co_u32_e32 v5, vcc, 0, v3, vcc
	v_add_co_u32_e32 v6, vcc, s5, v2
	s_mov_b32 s5, 0x28000
	s_nop 0
	v_addc_co_u32_e32 v7, vcc, 0, v3, vcc
	global_load_dwordx4 v[90:93], v[4:5], off nt
	global_load_dwordx4 v[94:97], v[6:7], off nt
	v_add_co_u32_e32 v4, vcc, s5, v2
	s_mov_b32 s5, 0x30000
	s_nop 0
	v_addc_co_u32_e32 v5, vcc, 0, v3, vcc
	v_add_co_u32_e32 v6, vcc, s58, v2
	s_lshl_b32 s4, s4, 11
	s_nop 0
	v_addc_co_u32_e32 v7, vcc, 0, v3, vcc
	global_load_dwordx4 v[82:85], v[4:5], off nt
	global_load_dwordx4 v[86:89], v[6:7], off nt
	v_add_co_u32_e32 v4, vcc, s5, v2
	s_mov_b32 s5, 0x32000
	s_nop 0
	v_addc_co_u32_e32 v5, vcc, 0, v3, vcc
	v_add_co_u32_e32 v6, vcc, s5, v2
	s_mov_b32 s5, 0x3a000
	s_nop 0
	v_addc_co_u32_e32 v7, vcc, 0, v3, vcc
	global_load_dwordx4 v[74:77], v[4:5], off nt
	global_load_dwordx4 v[78:81], v[6:7], off nt
	v_add_co_u32_e32 v4, vcc, s61, v2
	s_mov_b64 s[44:45], 0x2c00000
	s_nop 0
	v_addc_co_u32_e32 v5, vcc, 0, v3, vcc
	v_add_co_u32_e32 v6, vcc, s5, v2
	s_mov_b32 s5, 0x40000
	s_nop 0
	v_addc_co_u32_e32 v7, vcc, 0, v3, vcc
	global_load_dwordx4 v[66:69], v[4:5], off nt
	global_load_dwordx4 v[70:73], v[6:7], off nt
	v_add_co_u32_e32 v4, vcc, s5, v2
	s_mov_b32 s5, 0x42000
	s_nop 0
	v_addc_co_u32_e32 v5, vcc, 0, v3, vcc
	v_add_co_u32_e32 v6, vcc, s5, v2
	s_mov_b32 s5, 0x48000
	s_nop 0
	v_addc_co_u32_e32 v7, vcc, 0, v3, vcc
	global_load_dwordx4 v[58:61], v[4:5], off nt
	global_load_dwordx4 v[62:65], v[6:7], off nt
	v_add_co_u32_e32 v4, vcc, s5, v2
	s_mov_b32 s5, 0x4a000
	s_nop 0
	v_addc_co_u32_e32 v5, vcc, 0, v3, vcc
	v_add_co_u32_e32 v6, vcc, s5, v2
	s_mov_b32 s5, 0x50000
	s_nop 0
	v_addc_co_u32_e32 v7, vcc, 0, v3, vcc
	global_load_dwordx4 v[50:53], v[4:5], off nt
	global_load_dwordx4 v[54:57], v[6:7], off nt
	v_add_co_u32_e32 v4, vcc, s5, v2
	s_waitcnt vmcnt(19)
	v_bfe_u32 v132, v106, 17, 1
	v_addc_co_u32_e32 v5, vcc, 0, v3, vcc
	v_add_co_u32_e32 v6, vcc, s75, v2
	v_add3_u32 v106, v106, v132, s86
	s_nop 0
	v_addc_co_u32_e32 v7, vcc, 0, v3, vcc
	global_load_dwordx4 v[42:45], v[4:5], off nt
	global_load_dwordx4 v[46:49], v[6:7], off nt
	v_add_co_u32_e32 v4, vcc, s76, v2
	s_waitcnt vmcnt(20)
	v_bfe_u32 v132, v110, 17, 1
	v_addc_co_u32_e32 v5, vcc, 0, v3, vcc
	v_add_co_u32_e32 v6, vcc, s77, v2
	v_add3_u32 v110, v110, v132, s86
	s_nop 0
	v_addc_co_u32_e32 v7, vcc, 0, v3, vcc
	global_load_dwordx4 v[34:37], v[4:5], off nt
	global_load_dwordx4 v[38:41], v[6:7], off nt
	v_add_co_u32_e32 v4, vcc, s78, v2
	v_and_b32_e32 v106, 0xfffe0000, v106
	s_nop 0
	v_addc_co_u32_e32 v5, vcc, 0, v3, vcc
	v_add_co_u32_e32 v6, vcc, s79, v2
	v_and_b32_e32 v110, 0xfffe0000, v110
	s_nop 0
	v_addc_co_u32_e32 v7, vcc, 0, v3, vcc
	global_load_dwordx4 v[26:29], v[4:5], off nt
	global_load_dwordx4 v[30:33], v[6:7], off nt
	v_add_co_u32_e32 v4, vcc, s80, v2
	v_lshlrev_b32_e32 v132, 1, v134
	s_nop 0
	v_addc_co_u32_e32 v5, vcc, 0, v3, vcc
	v_add_co_u32_e32 v6, vcc, s81, v2
	s_nop 1
	v_addc_co_u32_e32 v7, vcc, 0, v3, vcc
	global_load_dwordx4 v[18:21], v[4:5], off nt
	global_load_dwordx4 v[22:25], v[6:7], off nt
	v_add_co_u32_e32 v4, vcc, s82, v2
	s_nop 1
	v_addc_co_u32_e32 v5, vcc, 0, v3, vcc
	v_add_co_u32_e32 v6, vcc, s83, v2
	s_nop 1
	v_addc_co_u32_e32 v7, vcc, 0, v3, vcc
	global_load_dwordx4 v[10:13], v[4:5], off nt
	global_load_dwordx4 v[14:17], v[6:7], off nt
	v_add_co_u32_e32 v4, vcc, s84, v2
	s_nop 1
	v_addc_co_u32_e32 v5, vcc, 0, v3, vcc
	v_add_co_u32_e32 v6, vcc, s85, v2
	s_nop 1
	v_addc_co_u32_e32 v7, vcc, 0, v3, vcc
	global_load_dwordx4 v[2:5], v[4:5], off nt
	s_nop 0
	global_load_dwordx4 v[6:9], v[6:7], off nt
	v_cvt_pk_bf16_f32 v106, v106, v110
	v_add_u32_e32 v110, v142, v143
	ds_write_b32 v110, v106
	v_bfe_u32 v106, v107, 17, 1
	v_add3_u32 v106, v107, v106, s86
	v_bfe_u32 v107, v111, 17, 1
	v_and_b32_e32 v106, 0xfffe0000, v106
	v_add3_u32 v107, v111, v107, s86
	v_and_b32_e32 v107, 0xfffe0000, v107
	v_cvt_pk_bf16_f32 v106, v106, v107
	ds_write_b32 v110, v106 offset:128
	v_bfe_u32 v106, v108, 17, 1
	v_add3_u32 v106, v108, v106, s86
	v_bfe_u32 v107, v112, 17, 1
	v_and_b32_e32 v106, 0xfffe0000, v106
	v_add3_u32 v107, v112, v107, s86
	v_and_b32_e32 v107, 0xfffe0000, v107
	v_cvt_pk_bf16_f32 v106, v106, v107
	ds_write_b32 v110, v106 offset:256
	v_bfe_u32 v106, v109, 17, 1
	v_add3_u32 v106, v109, v106, s86
	v_bfe_u32 v107, v113, 17, 1
	v_and_b32_e32 v106, 0xfffe0000, v106
	v_add3_u32 v107, v113, v107, s86
	v_and_b32_e32 v107, 0xfffe0000, v107
	v_cvt_pk_bf16_f32 v106, v106, v107
	ds_write_b32 v110, v106 offset:384
	s_waitcnt vmcnt(29)
	v_bfe_u32 v106, v114, 17, 1
	v_add3_u32 v106, v114, v106, s86
	s_waitcnt vmcnt(28)
	v_bfe_u32 v107, v118, 17, 1
	v_and_b32_e32 v106, 0xfffe0000, v106
	v_add3_u32 v107, v118, v107, s86
	v_and_b32_e32 v107, 0xfffe0000, v107
	v_cvt_pk_bf16_f32 v106, v106, v107
	ds_write_b32 v110, v106 offset:1032
	v_bfe_u32 v106, v115, 17, 1
	v_add3_u32 v106, v115, v106, s86
	v_bfe_u32 v107, v119, 17, 1
	v_and_b32_e32 v106, 0xfffe0000, v106
	v_add3_u32 v107, v119, v107, s86
	v_and_b32_e32 v107, 0xfffe0000, v107
	v_cvt_pk_bf16_f32 v106, v106, v107
	ds_write_b32 v110, v106 offset:1160
	v_bfe_u32 v106, v116, 17, 1
	v_add3_u32 v106, v116, v106, s86
	v_bfe_u32 v107, v120, 17, 1
	v_and_b32_e32 v106, 0xfffe0000, v106
	v_add3_u32 v107, v120, v107, s86
	v_and_b32_e32 v107, 0xfffe0000, v107
	v_cvt_pk_bf16_f32 v106, v106, v107
	ds_write_b32 v110, v106 offset:1288
	v_bfe_u32 v106, v117, 17, 1
	v_add3_u32 v106, v117, v106, s86
	v_bfe_u32 v107, v121, 17, 1
	v_and_b32_e32 v106, 0xfffe0000, v106
	v_add3_u32 v107, v121, v107, s86
	v_and_b32_e32 v107, 0xfffe0000, v107
	v_cvt_pk_bf16_f32 v106, v106, v107
	ds_write_b32 v110, v106 offset:1416
	s_waitcnt vmcnt(27)
	v_bfe_u32 v106, v122, 17, 1
	v_add3_u32 v106, v122, v106, s86
	s_waitcnt vmcnt(26)
	v_bfe_u32 v107, v126, 17, 1
	v_and_b32_e32 v106, 0xfffe0000, v106
	v_add3_u32 v107, v126, v107, s86
	v_and_b32_e32 v107, 0xfffe0000, v107
	v_cvt_pk_bf16_f32 v106, v106, v107
	ds_write_b32 v110, v106 offset:2064
	v_bfe_u32 v106, v123, 17, 1
	v_add3_u32 v106, v123, v106, s86
	v_bfe_u32 v107, v127, 17, 1
	v_and_b32_e32 v106, 0xfffe0000, v106
	v_add3_u32 v107, v127, v107, s86
	v_and_b32_e32 v107, 0xfffe0000, v107
	v_cvt_pk_bf16_f32 v106, v106, v107
	ds_write_b32 v110, v106 offset:2192
	v_bfe_u32 v106, v124, 17, 1
	v_add3_u32 v106, v124, v106, s86
	v_bfe_u32 v107, v128, 17, 1
	v_and_b32_e32 v106, 0xfffe0000, v106
	v_add3_u32 v107, v128, v107, s86
	v_and_b32_e32 v107, 0xfffe0000, v107
	v_cvt_pk_bf16_f32 v106, v106, v107
	ds_write_b32 v110, v106 offset:2320
	v_bfe_u32 v106, v125, 17, 1
	v_add3_u32 v106, v125, v106, s86
	v_bfe_u32 v107, v129, 17, 1
	v_and_b32_e32 v106, 0xfffe0000, v106
	v_add3_u32 v107, v129, v107, s86
	v_and_b32_e32 v107, 0xfffe0000, v107
	v_cvt_pk_bf16_f32 v106, v106, v107
	ds_write_b32 v110, v106 offset:2448
	s_waitcnt vmcnt(25)
	v_bfe_u32 v106, v98, 17, 1
	v_add3_u32 v98, v98, v106, s86
	s_waitcnt vmcnt(24)
	v_bfe_u32 v106, v102, 17, 1
	v_and_b32_e32 v98, 0xfffe0000, v98
	v_add3_u32 v102, v102, v106, s86
	v_and_b32_e32 v102, 0xfffe0000, v102
	v_cvt_pk_bf16_f32 v98, v98, v102
	ds_write_b32 v110, v98 offset:3096
	v_bfe_u32 v98, v99, 17, 1
	v_add3_u32 v98, v99, v98, s86
	v_bfe_u32 v99, v103, 17, 1
	v_and_b32_e32 v98, 0xfffe0000, v98
	v_add3_u32 v99, v103, v99, s86
	v_and_b32_e32 v99, 0xfffe0000, v99
	v_cvt_pk_bf16_f32 v98, v98, v99
	ds_write_b32 v110, v98 offset:3224
	v_bfe_u32 v98, v100, 17, 1
	v_add3_u32 v98, v100, v98, s86
	v_bfe_u32 v99, v104, 17, 1
	v_and_b32_e32 v98, 0xfffe0000, v98
	v_add3_u32 v99, v104, v99, s86
	v_and_b32_e32 v99, 0xfffe0000, v99
	v_cvt_pk_bf16_f32 v98, v98, v99
	ds_write_b32 v110, v98 offset:3352
	v_bfe_u32 v98, v101, 17, 1
	v_add3_u32 v98, v101, v98, s86
	v_bfe_u32 v99, v105, 17, 1
	v_and_b32_e32 v98, 0xfffe0000, v98
	v_add3_u32 v99, v105, v99, s86
	v_and_b32_e32 v99, 0xfffe0000, v99
	v_cvt_pk_bf16_f32 v98, v98, v99
	ds_write_b32 v110, v98 offset:3480
	s_waitcnt vmcnt(23)
	v_bfe_u32 v98, v90, 17, 1
	v_add3_u32 v90, v90, v98, s86
	s_waitcnt vmcnt(22)
	v_bfe_u32 v98, v94, 17, 1
	v_and_b32_e32 v90, 0xfffe0000, v90
	v_add3_u32 v94, v94, v98, s86
	v_and_b32_e32 v94, 0xfffe0000, v94
	v_cvt_pk_bf16_f32 v90, v90, v94
	ds_write_b32 v110, v90 offset:4128
	v_bfe_u32 v90, v91, 17, 1
	v_add3_u32 v90, v91, v90, s86
	v_bfe_u32 v91, v95, 17, 1
	v_and_b32_e32 v90, 0xfffe0000, v90
	v_add3_u32 v91, v95, v91, s86
	v_and_b32_e32 v91, 0xfffe0000, v91
	v_cvt_pk_bf16_f32 v90, v90, v91
	ds_write_b32 v110, v90 offset:4256
	v_bfe_u32 v90, v92, 17, 1
	v_add3_u32 v90, v92, v90, s86
	v_bfe_u32 v91, v96, 17, 1
	v_and_b32_e32 v90, 0xfffe0000, v90
	v_add3_u32 v91, v96, v91, s86
	v_and_b32_e32 v91, 0xfffe0000, v91
	v_cvt_pk_bf16_f32 v90, v90, v91
	ds_write_b32 v110, v90 offset:4384
	v_bfe_u32 v90, v93, 17, 1
	v_add3_u32 v90, v93, v90, s86
	v_bfe_u32 v91, v97, 17, 1
	v_and_b32_e32 v90, 0xfffe0000, v90
	v_add3_u32 v91, v97, v91, s86
	v_and_b32_e32 v91, 0xfffe0000, v91
	v_cvt_pk_bf16_f32 v90, v90, v91
	ds_write_b32 v110, v90 offset:4512
	s_waitcnt vmcnt(21)
	v_bfe_u32 v90, v82, 17, 1
	v_add3_u32 v82, v82, v90, s86
	s_waitcnt vmcnt(20)
	v_bfe_u32 v90, v86, 17, 1
	v_and_b32_e32 v82, 0xfffe0000, v82
	v_add3_u32 v86, v86, v90, s86
	v_and_b32_e32 v86, 0xfffe0000, v86
	v_cvt_pk_bf16_f32 v82, v82, v86
	ds_write_b32 v110, v82 offset:5160
	v_bfe_u32 v82, v83, 17, 1
	v_add3_u32 v82, v83, v82, s86
	v_bfe_u32 v83, v87, 17, 1
	v_and_b32_e32 v82, 0xfffe0000, v82
	v_add3_u32 v83, v87, v83, s86
	v_and_b32_e32 v83, 0xfffe0000, v83
	v_cvt_pk_bf16_f32 v82, v82, v83
	ds_write_b32 v110, v82 offset:5288
	v_bfe_u32 v82, v84, 17, 1
	v_add3_u32 v82, v84, v82, s86
	v_bfe_u32 v83, v88, 17, 1
	v_and_b32_e32 v82, 0xfffe0000, v82
	v_add3_u32 v83, v88, v83, s86
	v_and_b32_e32 v83, 0xfffe0000, v83
	v_cvt_pk_bf16_f32 v82, v82, v83
	ds_write_b32 v110, v82 offset:5416
	v_bfe_u32 v82, v85, 17, 1
	v_add3_u32 v82, v85, v82, s86
	v_bfe_u32 v83, v89, 17, 1
	v_and_b32_e32 v82, 0xfffe0000, v82
	v_add3_u32 v83, v89, v83, s86
	v_and_b32_e32 v83, 0xfffe0000, v83
	v_cvt_pk_bf16_f32 v82, v82, v83
	ds_write_b32 v110, v82 offset:5544
	s_waitcnt vmcnt(19)
	v_bfe_u32 v82, v74, 17, 1
	v_add3_u32 v74, v74, v82, s86
	s_waitcnt vmcnt(18)
	v_bfe_u32 v82, v78, 17, 1
	v_and_b32_e32 v74, 0xfffe0000, v74
	v_add3_u32 v78, v78, v82, s86
	v_and_b32_e32 v78, 0xfffe0000, v78
	v_cvt_pk_bf16_f32 v74, v74, v78
	ds_write_b32 v110, v74 offset:6192
	v_bfe_u32 v74, v75, 17, 1
	v_add3_u32 v74, v75, v74, s86
	v_bfe_u32 v75, v79, 17, 1
	v_and_b32_e32 v74, 0xfffe0000, v74
	v_add3_u32 v75, v79, v75, s86
	v_and_b32_e32 v75, 0xfffe0000, v75
	v_cvt_pk_bf16_f32 v74, v74, v75
	ds_write_b32 v110, v74 offset:6320
	v_bfe_u32 v74, v76, 17, 1
	v_add3_u32 v74, v76, v74, s86
	v_bfe_u32 v75, v80, 17, 1
	v_and_b32_e32 v74, 0xfffe0000, v74
	v_add3_u32 v75, v80, v75, s86
	v_and_b32_e32 v75, 0xfffe0000, v75
	v_cvt_pk_bf16_f32 v74, v74, v75
	ds_write_b32 v110, v74 offset:6448
	v_bfe_u32 v74, v77, 17, 1
	v_add3_u32 v74, v77, v74, s86
	v_bfe_u32 v75, v81, 17, 1
	v_and_b32_e32 v74, 0xfffe0000, v74
	v_add3_u32 v75, v81, v75, s86
	v_and_b32_e32 v75, 0xfffe0000, v75
	v_cvt_pk_bf16_f32 v74, v74, v75
	ds_write_b32 v110, v74 offset:6576
	s_waitcnt vmcnt(17)
	v_bfe_u32 v74, v66, 17, 1
	v_add3_u32 v66, v66, v74, s86
	s_waitcnt vmcnt(16)
	v_bfe_u32 v74, v70, 17, 1
	v_and_b32_e32 v66, 0xfffe0000, v66
	v_add3_u32 v70, v70, v74, s86
	v_and_b32_e32 v70, 0xfffe0000, v70
	v_cvt_pk_bf16_f32 v66, v66, v70
	ds_write_b32 v110, v66 offset:7224
	v_bfe_u32 v66, v67, 17, 1
	v_add3_u32 v66, v67, v66, s86
	v_bfe_u32 v67, v71, 17, 1
	v_and_b32_e32 v66, 0xfffe0000, v66
	v_add3_u32 v67, v71, v67, s86
	v_and_b32_e32 v67, 0xfffe0000, v67
	v_cvt_pk_bf16_f32 v66, v66, v67
	ds_write_b32 v110, v66 offset:7352
	v_bfe_u32 v66, v68, 17, 1
	v_add3_u32 v66, v68, v66, s86
	v_bfe_u32 v67, v72, 17, 1
	v_and_b32_e32 v66, 0xfffe0000, v66
	v_add3_u32 v67, v72, v67, s86
	v_and_b32_e32 v67, 0xfffe0000, v67
	v_cvt_pk_bf16_f32 v66, v66, v67
	ds_write_b32 v110, v66 offset:7480
	v_bfe_u32 v66, v69, 17, 1
	v_add3_u32 v66, v69, v66, s86
	v_bfe_u32 v67, v73, 17, 1
	v_and_b32_e32 v66, 0xfffe0000, v66
	v_add3_u32 v67, v73, v67, s86
	v_and_b32_e32 v67, 0xfffe0000, v67
	v_cvt_pk_bf16_f32 v66, v66, v67
	ds_write_b32 v110, v66 offset:7608
	s_waitcnt vmcnt(15)
	v_bfe_u32 v66, v58, 17, 1
	v_add3_u32 v58, v58, v66, s86
	s_waitcnt vmcnt(14)
	v_bfe_u32 v66, v62, 17, 1
	v_and_b32_e32 v58, 0xfffe0000, v58
	v_add3_u32 v62, v62, v66, s86
	v_and_b32_e32 v62, 0xfffe0000, v62
	v_cvt_pk_bf16_f32 v58, v58, v62
	ds_write_b32 v110, v58 offset:8256
	v_bfe_u32 v58, v59, 17, 1
	v_add3_u32 v58, v59, v58, s86
	v_bfe_u32 v59, v63, 17, 1
	v_and_b32_e32 v58, 0xfffe0000, v58
	v_add3_u32 v59, v63, v59, s86
	v_and_b32_e32 v59, 0xfffe0000, v59
	v_cvt_pk_bf16_f32 v58, v58, v59
	ds_write_b32 v110, v58 offset:8384
	v_bfe_u32 v58, v60, 17, 1
	v_add3_u32 v58, v60, v58, s86
	v_bfe_u32 v59, v64, 17, 1
	v_and_b32_e32 v58, 0xfffe0000, v58
	v_add3_u32 v59, v64, v59, s86
	v_and_b32_e32 v59, 0xfffe0000, v59
	v_cvt_pk_bf16_f32 v58, v58, v59
	ds_write_b32 v110, v58 offset:8512
	v_bfe_u32 v58, v61, 17, 1
	v_add3_u32 v58, v61, v58, s86
	v_bfe_u32 v59, v65, 17, 1
	v_and_b32_e32 v58, 0xfffe0000, v58
	v_add3_u32 v59, v65, v59, s86
	v_and_b32_e32 v59, 0xfffe0000, v59
	v_cvt_pk_bf16_f32 v58, v58, v59
	ds_write_b32 v110, v58 offset:8640
	s_waitcnt vmcnt(13)
	v_bfe_u32 v58, v50, 17, 1
	v_add3_u32 v50, v50, v58, s86
	s_waitcnt vmcnt(12)
	v_bfe_u32 v58, v54, 17, 1
	v_and_b32_e32 v50, 0xfffe0000, v50
	v_add3_u32 v54, v54, v58, s86
	v_and_b32_e32 v54, 0xfffe0000, v54
	v_cvt_pk_bf16_f32 v50, v50, v54
	ds_write_b32 v110, v50 offset:9288
	v_bfe_u32 v50, v51, 17, 1
	v_add3_u32 v50, v51, v50, s86
	v_bfe_u32 v51, v55, 17, 1
	v_and_b32_e32 v50, 0xfffe0000, v50
	v_add3_u32 v51, v55, v51, s86
	v_and_b32_e32 v51, 0xfffe0000, v51
	v_cvt_pk_bf16_f32 v50, v50, v51
	ds_write_b32 v110, v50 offset:9416
	v_bfe_u32 v50, v52, 17, 1
	v_add3_u32 v50, v52, v50, s86
	v_bfe_u32 v51, v56, 17, 1
	v_and_b32_e32 v50, 0xfffe0000, v50
	v_add3_u32 v51, v56, v51, s86
	v_and_b32_e32 v51, 0xfffe0000, v51
	v_cvt_pk_bf16_f32 v50, v50, v51
	ds_write_b32 v110, v50 offset:9544
	v_bfe_u32 v50, v53, 17, 1
	v_add3_u32 v50, v53, v50, s86
	v_bfe_u32 v51, v57, 17, 1
	v_and_b32_e32 v50, 0xfffe0000, v50
	v_add3_u32 v51, v57, v51, s86
	v_and_b32_e32 v51, 0xfffe0000, v51
	v_cvt_pk_bf16_f32 v50, v50, v51
	ds_write_b32 v110, v50 offset:9672
	s_waitcnt vmcnt(11)
	v_bfe_u32 v50, v42, 17, 1
	v_add3_u32 v42, v42, v50, s86
	s_waitcnt vmcnt(10)
	v_bfe_u32 v50, v46, 17, 1
	v_and_b32_e32 v42, 0xfffe0000, v42
	v_add3_u32 v46, v46, v50, s86
	v_and_b32_e32 v46, 0xfffe0000, v46
	v_cvt_pk_bf16_f32 v42, v42, v46
	ds_write_b32 v110, v42 offset:10320
	v_bfe_u32 v42, v43, 17, 1
	v_add3_u32 v42, v43, v42, s86
	v_bfe_u32 v43, v47, 17, 1
	v_and_b32_e32 v42, 0xfffe0000, v42
	v_add3_u32 v43, v47, v43, s86
	v_and_b32_e32 v43, 0xfffe0000, v43
	v_cvt_pk_bf16_f32 v42, v42, v43
	ds_write_b32 v110, v42 offset:10448
	v_bfe_u32 v42, v44, 17, 1
	v_add3_u32 v42, v44, v42, s86
	v_bfe_u32 v43, v48, 17, 1
	v_and_b32_e32 v42, 0xfffe0000, v42
	v_add3_u32 v43, v48, v43, s86
	v_and_b32_e32 v43, 0xfffe0000, v43
	v_cvt_pk_bf16_f32 v42, v42, v43
	ds_write_b32 v110, v42 offset:10576
	v_bfe_u32 v42, v45, 17, 1
	v_add3_u32 v42, v45, v42, s86
	v_bfe_u32 v43, v49, 17, 1
	v_and_b32_e32 v42, 0xfffe0000, v42
	v_add3_u32 v43, v49, v43, s86
	v_and_b32_e32 v43, 0xfffe0000, v43
	v_cvt_pk_bf16_f32 v42, v42, v43
	ds_write_b32 v110, v42 offset:10704
	s_waitcnt vmcnt(9)
	v_bfe_u32 v42, v34, 17, 1
	v_add3_u32 v34, v34, v42, s86
	s_waitcnt vmcnt(8)
	v_bfe_u32 v42, v38, 17, 1
	v_and_b32_e32 v34, 0xfffe0000, v34
	v_add3_u32 v38, v38, v42, s86
	v_and_b32_e32 v38, 0xfffe0000, v38
	v_cvt_pk_bf16_f32 v34, v34, v38
	ds_write_b32 v110, v34 offset:11352
	v_bfe_u32 v34, v35, 17, 1
	v_add3_u32 v34, v35, v34, s86
	v_bfe_u32 v35, v39, 17, 1
	v_and_b32_e32 v34, 0xfffe0000, v34
	v_add3_u32 v35, v39, v35, s86
	v_and_b32_e32 v35, 0xfffe0000, v35
	v_cvt_pk_bf16_f32 v34, v34, v35
	ds_write_b32 v110, v34 offset:11480
	v_bfe_u32 v34, v36, 17, 1
	v_add3_u32 v34, v36, v34, s86
	v_bfe_u32 v35, v40, 17, 1
	v_and_b32_e32 v34, 0xfffe0000, v34
	v_add3_u32 v35, v40, v35, s86
	v_and_b32_e32 v35, 0xfffe0000, v35
	v_cvt_pk_bf16_f32 v34, v34, v35
	ds_write_b32 v110, v34 offset:11608
	v_bfe_u32 v34, v37, 17, 1
	v_add3_u32 v34, v37, v34, s86
	v_bfe_u32 v35, v41, 17, 1
	v_and_b32_e32 v34, 0xfffe0000, v34
	v_add3_u32 v35, v41, v35, s86
	v_and_b32_e32 v35, 0xfffe0000, v35
	v_cvt_pk_bf16_f32 v34, v34, v35
	ds_write_b32 v110, v34 offset:11736
	s_waitcnt vmcnt(7)
	v_bfe_u32 v34, v26, 17, 1
	v_add3_u32 v26, v26, v34, s86
	s_waitcnt vmcnt(6)
	v_bfe_u32 v34, v30, 17, 1
	v_and_b32_e32 v26, 0xfffe0000, v26
	v_add3_u32 v30, v30, v34, s86
	v_and_b32_e32 v30, 0xfffe0000, v30
	v_cvt_pk_bf16_f32 v26, v26, v30
	ds_write_b32 v110, v26 offset:12384
	v_bfe_u32 v26, v27, 17, 1
	v_add3_u32 v26, v27, v26, s86
	v_bfe_u32 v27, v31, 17, 1
	v_and_b32_e32 v26, 0xfffe0000, v26
	v_add3_u32 v27, v31, v27, s86
	v_and_b32_e32 v27, 0xfffe0000, v27
	v_cvt_pk_bf16_f32 v26, v26, v27
	ds_write_b32 v110, v26 offset:12512
	v_bfe_u32 v26, v28, 17, 1
	v_add3_u32 v26, v28, v26, s86
	v_bfe_u32 v27, v32, 17, 1
	v_and_b32_e32 v26, 0xfffe0000, v26
	v_add3_u32 v27, v32, v27, s86
	v_and_b32_e32 v27, 0xfffe0000, v27
	v_cvt_pk_bf16_f32 v26, v26, v27
	ds_write_b32 v110, v26 offset:12640
	v_bfe_u32 v26, v29, 17, 1
	v_add3_u32 v26, v29, v26, s86
	v_bfe_u32 v27, v33, 17, 1
	v_and_b32_e32 v26, 0xfffe0000, v26
	v_add3_u32 v27, v33, v27, s86
	v_and_b32_e32 v27, 0xfffe0000, v27
	v_cvt_pk_bf16_f32 v26, v26, v27
	ds_write_b32 v110, v26 offset:12768
	s_waitcnt vmcnt(5)
	v_bfe_u32 v26, v18, 17, 1
	v_add3_u32 v18, v18, v26, s86
	s_waitcnt vmcnt(4)
	v_bfe_u32 v26, v22, 17, 1
	v_and_b32_e32 v18, 0xfffe0000, v18
	v_add3_u32 v22, v22, v26, s86
	v_and_b32_e32 v22, 0xfffe0000, v22
	v_cvt_pk_bf16_f32 v18, v18, v22
	ds_write_b32 v110, v18 offset:13416
	v_bfe_u32 v18, v19, 17, 1
	v_add3_u32 v18, v19, v18, s86
	v_bfe_u32 v19, v23, 17, 1
	v_and_b32_e32 v18, 0xfffe0000, v18
	v_add3_u32 v19, v23, v19, s86
	v_and_b32_e32 v19, 0xfffe0000, v19
	v_cvt_pk_bf16_f32 v18, v18, v19
	ds_write_b32 v110, v18 offset:13544
	v_bfe_u32 v18, v20, 17, 1
	v_add3_u32 v18, v20, v18, s86
	v_bfe_u32 v19, v24, 17, 1
	v_and_b32_e32 v18, 0xfffe0000, v18
	v_add3_u32 v19, v24, v19, s86
	v_and_b32_e32 v19, 0xfffe0000, v19
	v_cvt_pk_bf16_f32 v18, v18, v19
	ds_write_b32 v110, v18 offset:13672
	v_bfe_u32 v18, v21, 17, 1
	v_add3_u32 v18, v21, v18, s86
	v_bfe_u32 v19, v25, 17, 1
	v_and_b32_e32 v18, 0xfffe0000, v18
	v_add3_u32 v19, v25, v19, s86
	v_and_b32_e32 v19, 0xfffe0000, v19
	v_cvt_pk_bf16_f32 v18, v18, v19
	ds_write_b32 v110, v18 offset:13800
	s_waitcnt vmcnt(3)
	v_bfe_u32 v18, v10, 17, 1
	v_add3_u32 v10, v10, v18, s86
	s_waitcnt vmcnt(2)
	v_bfe_u32 v18, v14, 17, 1
	v_and_b32_e32 v10, 0xfffe0000, v10
	v_add3_u32 v14, v14, v18, s86
	v_and_b32_e32 v14, 0xfffe0000, v14
	v_cvt_pk_bf16_f32 v10, v10, v14
	ds_write_b32 v110, v10 offset:14448
	v_bfe_u32 v10, v11, 17, 1
	v_add3_u32 v10, v11, v10, s86
	v_bfe_u32 v11, v15, 17, 1
	v_and_b32_e32 v10, 0xfffe0000, v10
	v_add3_u32 v11, v15, v11, s86
	v_and_b32_e32 v11, 0xfffe0000, v11
	v_cvt_pk_bf16_f32 v10, v10, v11
	ds_write_b32 v110, v10 offset:14576
	v_bfe_u32 v10, v12, 17, 1
	v_add3_u32 v10, v12, v10, s86
	v_bfe_u32 v11, v16, 17, 1
	v_and_b32_e32 v10, 0xfffe0000, v10
	v_add3_u32 v11, v16, v11, s86
	v_and_b32_e32 v11, 0xfffe0000, v11
	v_cvt_pk_bf16_f32 v10, v10, v11
	ds_write_b32 v110, v10 offset:14704
	v_bfe_u32 v10, v13, 17, 1
	v_add3_u32 v10, v13, v10, s86
	v_bfe_u32 v11, v17, 17, 1
	v_and_b32_e32 v10, 0xfffe0000, v10
	v_add3_u32 v11, v17, v11, s86
	v_and_b32_e32 v11, 0xfffe0000, v11
	v_cvt_pk_bf16_f32 v10, v10, v11
	ds_write_b32 v110, v10 offset:14832
	s_waitcnt vmcnt(1)
	v_bfe_u32 v10, v2, 17, 1
	v_add3_u32 v2, v2, v10, s86
	s_waitcnt vmcnt(0)
	v_bfe_u32 v10, v6, 17, 1
	v_and_b32_e32 v2, 0xfffe0000, v2
	v_add3_u32 v6, v6, v10, s86
	v_and_b32_e32 v6, 0xfffe0000, v6
	v_cvt_pk_bf16_f32 v2, v2, v6
	ds_write_b32 v110, v2 offset:15480
	v_bfe_u32 v2, v3, 17, 1
	v_add3_u32 v2, v3, v2, s86
	v_bfe_u32 v3, v7, 17, 1
	v_and_b32_e32 v2, 0xfffe0000, v2
	v_add3_u32 v3, v7, v3, s86
	v_and_b32_e32 v3, 0xfffe0000, v3
	v_cvt_pk_bf16_f32 v2, v2, v3
	ds_write_b32 v110, v2 offset:15608
	v_bfe_u32 v2, v4, 17, 1
	v_add3_u32 v2, v4, v2, s86
	v_bfe_u32 v3, v8, 17, 1
	v_and_b32_e32 v2, 0xfffe0000, v2
	v_add3_u32 v3, v8, v3, s86
	v_and_b32_e32 v3, 0xfffe0000, v3
	v_cvt_pk_bf16_f32 v2, v2, v3
	ds_write_b32 v110, v2 offset:15736
	v_bfe_u32 v2, v5, 17, 1
	v_add3_u32 v2, v5, v2, s86
	v_bfe_u32 v3, v9, 17, 1
	v_and_b32_e32 v2, 0xfffe0000, v2
	v_add3_u32 v3, v9, v3, s86
	v_and_b32_e32 v3, 0xfffe0000, v3
	v_cvt_pk_bf16_f32 v2, v2, v3
	ds_write_b32 v110, v2 offset:15864
	s_waitcnt lgkmcnt(0)
	ds_read2_b32 v[20:21], v146 offset1:8
	ds_read2_b32 v[4:5], v146 offset0:129 offset1:137
	v_add_u32_e32 v30, 0x400, v146
	ds_read2_b32 v[22:23], v30 offset0:2 offset1:10
	ds_read2_b32 v[6:7], v30 offset0:131 offset1:139
	v_add_u32_e32 v32, 0x400, v147
	ds_read2_b32 v[24:25], v147 offset1:8
	ds_read2_b32 v[12:13], v147 offset0:129 offset1:137
	ds_read2_b32 v[26:27], v32 offset0:2 offset1:10
	ds_read2_b32 v[14:15], v32 offset0:131 offset1:139
	v_or_b32_e32 v31, s2, v131
	v_lshl_add_u64 v[2:3], s[40:41], 0, v[132:133]
	s_waitcnt lgkmcnt(6)
	v_mov_b32_e32 v9, v4
	v_or3_b32 v4, v31, v145, s4
	v_or_b32_e32 v33, s2, v144
	v_lshl_add_u64 v[2:3], v[2:3], 0, s[44:45]
	v_lshlrev_b32_e32 v132, 7, v4
	v_or3_b32 v4, v33, v145, s4
	v_mov_b32_e32 v8, v20
	s_waitcnt lgkmcnt(5)
	v_mov_b32_e32 v10, v22
	s_waitcnt lgkmcnt(4)
	v_mov_b32_e32 v11, v6
	v_lshl_add_u64 v[16:17], v[2:3], 0, v[132:133]
	v_lshlrev_b32_e32 v132, 7, v4
	global_store_dwordx4 v[16:17], v[8:11], off nt
	v_lshl_add_u64 v[16:17], v[2:3], 0, v[132:133]
	v_add_u32_e32 v4, 0x400, v149
	s_waitcnt lgkmcnt(3)
	v_mov_b32_e32 v8, v24
	s_waitcnt lgkmcnt(2)
	v_mov_b32_e32 v9, v12
	s_waitcnt lgkmcnt(1)
	v_mov_b32_e32 v10, v26
	s_waitcnt lgkmcnt(0)
	v_mov_b32_e32 v11, v14
	global_store_dwordx4 v[16:17], v[8:11], off nt
	ds_read2_b32 v[10:11], v4 offset0:2 offset1:131
	v_or3_b32 v4, v31, v148, s4
	ds_read2_b32 v[8:9], v149 offset1:129
	v_lshlrev_b32_e32 v132, 7, v4
	v_add_u32_e32 v4, 0x400, v150
	ds_read2_b32 v[16:17], v150 offset1:129
	ds_read2_b32 v[18:19], v4 offset0:2 offset1:131
	v_or3_b32 v4, v33, v148, s4
	v_lshl_add_u64 v[28:29], v[2:3], 0, v[132:133]
	v_lshlrev_b32_e32 v132, 7, v4
	s_waitcnt lgkmcnt(2)
	global_store_dwordx4 v[28:29], v[8:11], off nt
	v_mov_b32_e32 v4, v21
	v_mov_b32_e32 v6, v23
	v_lshl_add_u64 v[8:9], v[2:3], 0, v[132:133]
	s_waitcnt lgkmcnt(0)
	global_store_dwordx4 v[8:9], v[16:19], off nt
	v_or3_b32 v8, v31, v151, s4
	v_lshlrev_b32_e32 v132, 7, v8
	v_lshl_add_u64 v[8:9], v[2:3], 0, v[132:133]
	global_store_dwordx4 v[8:9], v[4:7], off nt
	v_mov_b32_e32 v12, v25
	v_mov_b32_e32 v14, v27
	v_or3_b32 v4, v33, v151, s4
	v_add_u32_e32 v6, 0x400, v153
	v_lshlrev_b32_e32 v132, 7, v4
	ds_read2_b32 v[4:5], v153 offset1:129
	ds_read2_b32 v[6:7], v6 offset0:2 offset1:131
	v_lshl_add_u64 v[8:9], v[2:3], 0, v[132:133]
	global_store_dwordx4 v[8:9], v[12:15], off nt
	v_or3_b32 v8, v31, v152, s4
	v_lshlrev_b32_e32 v132, 7, v8
	v_lshl_add_u64 v[8:9], v[2:3], 0, v[132:133]
	s_waitcnt lgkmcnt(0)
	global_store_dwordx4 v[8:9], v[4:7], off nt
	ds_read2_b32 v[4:5], v154 offset1:129
	v_or3_b32 v8, v33, v152, s4
	v_add_u32_e32 v6, 0x400, v154
	ds_read2_b32 v[6:7], v6 offset0:2 offset1:131
	v_lshlrev_b32_e32 v132, 7, v8
	v_lshl_add_u64 v[12:13], v[2:3], 0, v[132:133]
	ds_read2_b32 v[20:21], v146 offset0:16 offset1:24
	ds_read2_b32 v[8:9], v146 offset0:145 offset1:153
	ds_read2_b32 v[22:23], v30 offset0:18 offset1:26
	ds_read2_b32 v[10:11], v30 offset0:147 offset1:155
	s_waitcnt lgkmcnt(4)
	global_store_dwordx4 v[12:13], v[4:7], off nt
	ds_read2_b32 v[24:25], v147 offset0:16 offset1:24
	ds_read2_b32 v[12:13], v147 offset0:145 offset1:153
	ds_read2_b32 v[26:27], v32 offset0:18 offset1:26
	ds_read2_b32 v[14:15], v32 offset0:147 offset1:155
	s_waitcnt lgkmcnt(6)
	v_mov_b32_e32 v5, v8
	v_or3_b32 v8, v31, v155, s4
	v_lshlrev_b32_e32 v132, 7, v8
	v_or3_b32 v8, v33, v155, s4
	v_mov_b32_e32 v4, v20
	s_waitcnt lgkmcnt(5)
	v_mov_b32_e32 v6, v22
	s_waitcnt lgkmcnt(4)
	v_mov_b32_e32 v7, v10
	v_lshl_add_u64 v[16:17], v[2:3], 0, v[132:133]
	v_lshlrev_b32_e32 v132, 7, v8
	global_store_dwordx4 v[16:17], v[4:7], off nt
	v_lshl_add_u64 v[16:17], v[2:3], 0, v[132:133]
	v_or3_b32 v8, v31, v158, s4
	s_waitcnt lgkmcnt(3)
	v_mov_b32_e32 v4, v24
	s_waitcnt lgkmcnt(2)
	v_mov_b32_e32 v5, v12
	s_waitcnt lgkmcnt(1)
	v_mov_b32_e32 v6, v26
	s_waitcnt lgkmcnt(0)
	v_mov_b32_e32 v7, v14
	global_store_dwordx4 v[16:17], v[4:7], off nt
	ds_read2_b32 v[4:5], v159 offset1:129
	v_lshlrev_b32_e32 v132, 7, v8
	v_add_u32_e32 v6, 0x400, v159
	ds_read2_b32 v[6:7], v6 offset0:2 offset1:131
	v_add_u32_e32 v8, 0x400, v160
	ds_read2_b32 v[16:17], v160 offset1:129
	ds_read2_b32 v[18:19], v8 offset0:2 offset1:131
	v_lshl_add_u64 v[28:29], v[2:3], 0, v[132:133]
	s_waitcnt lgkmcnt(2)
	global_store_dwordx4 v[28:29], v[4:7], off nt
	v_mov_b32_e32 v8, v21
	v_mov_b32_e32 v10, v23
	v_or3_b32 v4, v33, v158, s4
	v_lshlrev_b32_e32 v132, 7, v4
	v_lshl_add_u64 v[4:5], v[2:3], 0, v[132:133]
	s_waitcnt lgkmcnt(0)
	global_store_dwordx4 v[4:5], v[16:19], off nt
	v_or3_b32 v4, v31, v161, s4
	v_lshlrev_b32_e32 v132, 7, v4
	v_lshl_add_u64 v[4:5], v[2:3], 0, v[132:133]
	global_store_dwordx4 v[4:5], v[8:11], off nt
	v_or3_b32 v4, v33, v161, s4
	v_lshlrev_b32_e32 v132, 7, v4
	v_mov_b32_e32 v12, v25
	v_mov_b32_e32 v14, v27
	v_lshl_add_u64 v[4:5], v[2:3], 0, v[132:133]
	v_add_u32_e32 v6, 0x400, v163
	global_store_dwordx4 v[4:5], v[12:15], off nt
	ds_read2_b32 v[4:5], v163 offset1:129
	ds_read2_b32 v[6:7], v6 offset0:2 offset1:131
	v_or3_b32 v8, v31, v162, s4
	v_add_u32_e32 v10, 0x400, v164
	v_lshlrev_b32_e32 v132, 7, v8
	ds_read2_b32 v[8:9], v164 offset1:129
	ds_read2_b32 v[10:11], v10 offset0:2 offset1:131
	v_lshl_add_u64 v[12:13], v[2:3], 0, v[132:133]
	s_waitcnt lgkmcnt(2)
	global_store_dwordx4 v[12:13], v[4:7], off nt
	s_nop 1
	v_or3_b32 v4, v33, v162, s4
	v_lshlrev_b32_e32 v132, 7, v4
	v_lshl_add_u64 v[2:3], v[2:3], 0, v[132:133]
	s_waitcnt lgkmcnt(0)
	global_store_dwordx4 v[2:3], v[8:11], off nt
	s_waitcnt lgkmcnt(0)

.LBB0_59:
	s_waitcnt vmcnt(0)
	v_mul_f32_e32 v6, v6, v18
	v_bfe_u32 v10, v6, 17, 1
	v_mul_f32_e32 v2, v2, v19
	v_add3_u32 v6, v6, v10, s86
	v_bfe_u32 v10, v2, 17, 1
	v_add3_u32 v2, v2, v10, s86
	v_and_b32_e32 v2, 0xfffe0000, v2
	v_and_b32_e32 v6, 0xfffe0000, v6
	v_cvt_pk_bf16_f32 v2, v6, v2
	ds_write_b32 v38, v2 offset:4128
	v_mul_f32_e32 v2, v7, v18
	v_bfe_u32 v6, v2, 17, 1
	v_mul_f32_e32 v3, v3, v19
	v_add3_u32 v2, v2, v6, s86
	v_bfe_u32 v6, v3, 17, 1
	v_and_b32_e32 v2, 0xfffe0000, v2
	v_add3_u32 v3, v3, v6, s86
	v_and_b32_e32 v3, 0xfffe0000, v3
	v_cvt_pk_bf16_f32 v2, v2, v3
	ds_write_b32 v38, v2 offset:4256
	v_mul_f32_e32 v2, v8, v18
	v_bfe_u32 v3, v2, 17, 1
	v_add3_u32 v2, v2, v3, s86
	v_mul_f32_e32 v3, v4, v19
	v_bfe_u32 v4, v3, 17, 1
	v_and_b32_e32 v2, 0xfffe0000, v2
	v_add3_u32 v3, v3, v4, s86
	v_and_b32_e32 v3, 0xfffe0000, v3
	v_cvt_pk_bf16_f32 v2, v2, v3
	ds_write_b32 v38, v2 offset:4384
	v_mul_f32_e32 v2, v9, v18
	v_bfe_u32 v3, v2, 17, 1
	v_add3_u32 v2, v2, v3, s86
	v_mul_f32_e32 v3, v5, v19
	v_bfe_u32 v4, v3, 17, 1
	v_and_b32_e32 v2, 0xfffe0000, v2
	v_add3_u32 v3, v3, v4, s86
	v_and_b32_e32 v3, 0xfffe0000, v3
	v_cvt_pk_bf16_f32 v2, v2, v3
	ds_write_b32 v38, v2 offset:4512
	s_waitcnt lgkmcnt(0)
	ds_read2_b32 v[16:17], v146 offset1:8
	ds_read2_b32 v[4:5], v146 offset0:129 offset1:137
	v_add_u32_e32 v26, 0x400, v146
	ds_read2_b32 v[18:19], v26 offset0:2 offset1:10
	ds_read2_b32 v[6:7], v26 offset0:131 offset1:139
	s_and_b32 s2, 0xffff, s71
	v_lshlrev_b32_e32 v132, 1, v134
	v_or_b32_e32 v27, s43, v131
	s_mulk_i32 s2, 0xe00
	v_lshl_add_u64 v[2:3], s[40:41], 0, v[132:133]
	s_mov_b64 s[4:5], 0x4200000
	s_waitcnt lgkmcnt(2)
	v_mov_b32_e32 v9, v4
	v_or_b32_e32 v4, v27, v145
	v_lshl_add_u64 v[2:3], v[2:3], 0, s[4:5]
	v_add_lshl_u32 v132, s2, v4, 7
	v_mov_b32_e32 v8, v16
	s_waitcnt lgkmcnt(1)
	v_mov_b32_e32 v10, v18
	s_waitcnt lgkmcnt(0)
	v_mov_b32_e32 v11, v6
	v_lshl_add_u64 v[12:13], v[2:3], 0, v[132:133]
	global_store_dwordx4 v[12:13], v[8:11], off nt
	v_add_u32_e32 v28, 0x400, v147
	ds_read2_b32 v[20:21], v147 offset1:8
	ds_read2_b32 v[8:9], v147 offset0:129 offset1:137
	ds_read2_b32 v[22:23], v28 offset0:2 offset1:10
	ds_read2_b32 v[10:11], v28 offset0:131 offset1:139
	v_or_b32_e32 v29, s43, v144
	v_or_b32_e32 v4, v29, v145
	v_add_lshl_u32 v132, s2, v4, 7
	s_waitcnt lgkmcnt(3)
	v_mov_b32_e32 v12, v20
	s_waitcnt lgkmcnt(2)
	v_mov_b32_e32 v13, v8
	s_waitcnt lgkmcnt(1)
	v_mov_b32_e32 v14, v22
	s_waitcnt lgkmcnt(0)
	v_mov_b32_e32 v15, v10
	v_lshl_add_u64 v[24:25], v[2:3], 0, v[132:133]
	v_add_u32_e32 v4, 0x400, v149
	global_store_dwordx4 v[24:25], v[12:15], off nt
	ds_read2_b32 v[12:13], v149 offset1:129
	ds_read2_b32 v[14:15], v4 offset0:2 offset1:131
	v_or_b32_e32 v4, v27, v148
	v_add_lshl_u32 v132, s2, v4, 7
	v_lshl_add_u64 v[24:25], v[2:3], 0, v[132:133]
	v_add_u32_e32 v4, 0x400, v150
	s_waitcnt lgkmcnt(0)
	global_store_dwordx4 v[24:25], v[12:15], off nt
	ds_read2_b32 v[12:13], v150 offset1:129
	ds_read2_b32 v[14:15], v4 offset0:2 offset1:131
	v_or_b32_e32 v4, v29, v148
	v_add_lshl_u32 v132, s2, v4, 7
	v_or_b32_e32 v8, v27, v151
	v_lshl_add_u64 v[24:25], v[2:3], 0, v[132:133]
	v_add_lshl_u32 v132, s2, v8, 7
	s_waitcnt lgkmcnt(0)
	global_store_dwordx4 v[24:25], v[12:15], off nt
	v_mov_b32_e32 v4, v17
	v_mov_b32_e32 v6, v19
	v_lshl_add_u64 v[12:13], v[2:3], 0, v[132:133]
	global_store_dwordx4 v[12:13], v[4:7], off nt
	v_mov_b32_e32 v8, v21
	v_mov_b32_e32 v10, v23
	v_or_b32_e32 v4, v29, v151
	v_add_lshl_u32 v132, s2, v4, 7
	v_lshl_add_u64 v[4:5], v[2:3], 0, v[132:133]
	v_add_u32_e32 v6, 0x400, v153
	global_store_dwordx4 v[4:5], v[8:11], off nt
	ds_read2_b32 v[4:5], v153 offset1:129
	ds_read2_b32 v[6:7], v6 offset0:2 offset1:131
	v_or_b32_e32 v8, v27, v152
	v_add_lshl_u32 v132, s2, v8, 7
	v_lshl_add_u64 v[8:9], v[2:3], 0, v[132:133]
	s_waitcnt lgkmcnt(0)
	global_store_dwordx4 v[8:9], v[4:7], off nt
	ds_read2_b32 v[4:5], v154 offset1:129
	s_nop 0
	v_add_u32_e32 v6, 0x400, v154
	ds_read2_b32 v[6:7], v6 offset0:2 offset1:131
	v_or_b32_e32 v8, v29, v152
	v_add_lshl_u32 v132, s2, v8, 7
	v_lshl_add_u64 v[8:9], v[2:3], 0, v[132:133]
	s_waitcnt lgkmcnt(0)
	global_store_dwordx4 v[8:9], v[4:7], off nt
	ds_read2_b32 v[16:17], v146 offset0:16 offset1:24
	ds_read2_b32 v[4:5], v146 offset0:145 offset1:153
	ds_read2_b32 v[18:19], v26 offset0:18 offset1:26
	ds_read2_b32 v[6:7], v26 offset0:147 offset1:155
	s_waitcnt lgkmcnt(3)
	v_mov_b32_e32 v8, v16
	s_waitcnt lgkmcnt(2)
	v_mov_b32_e32 v9, v4
	v_or_b32_e32 v4, v27, v155
	v_add_lshl_u32 v132, s2, v4, 7
	s_waitcnt lgkmcnt(1)
	v_mov_b32_e32 v10, v18
	s_waitcnt lgkmcnt(0)
	v_mov_b32_e32 v11, v6
	v_lshl_add_u64 v[12:13], v[2:3], 0, v[132:133]
	global_store_dwordx4 v[12:13], v[8:11], off nt
	ds_read2_b32 v[20:21], v147 offset0:16 offset1:24
	ds_read2_b32 v[8:9], v147 offset0:145 offset1:153
	ds_read2_b32 v[22:23], v28 offset0:18 offset1:26
	ds_read2_b32 v[10:11], v28 offset0:147 offset1:155
	v_or_b32_e32 v4, v29, v155
	v_add_lshl_u32 v132, s2, v4, 7
	s_waitcnt lgkmcnt(3)
	v_mov_b32_e32 v12, v20
	s_waitcnt lgkmcnt(2)
	v_mov_b32_e32 v13, v8
	s_waitcnt lgkmcnt(1)
	v_mov_b32_e32 v14, v22
	s_waitcnt lgkmcnt(0)
	v_mov_b32_e32 v15, v10
	v_lshl_add_u64 v[24:25], v[2:3], 0, v[132:133]
	v_add_u32_e32 v4, 0x400, v159
	global_store_dwordx4 v[24:25], v[12:15], off nt
	ds_read2_b32 v[12:13], v159 offset1:129
	ds_read2_b32 v[14:15], v4 offset0:2 offset1:131
	v_or_b32_e32 v4, v27, v158
	v_add_lshl_u32 v132, s2, v4, 7
	v_lshl_add_u64 v[24:25], v[2:3], 0, v[132:133]
	v_add_u32_e32 v4, 0x400, v160
	s_waitcnt lgkmcnt(0)
	global_store_dwordx4 v[24:25], v[12:15], off nt
	ds_read2_b32 v[12:13], v160 offset1:129
	ds_read2_b32 v[14:15], v4 offset0:2 offset1:131
	v_or_b32_e32 v4, v29, v158
	v_add_lshl_u32 v132, s2, v4, 7
	v_or_b32_e32 v8, v27, v161
	v_lshl_add_u64 v[24:25], v[2:3], 0, v[132:133]
	v_add_lshl_u32 v132, s2, v8, 7
	s_waitcnt lgkmcnt(0)
	global_store_dwordx4 v[24:25], v[12:15], off nt
	v_mov_b32_e32 v4, v17
	v_mov_b32_e32 v6, v19
	v_lshl_add_u64 v[12:13], v[2:3], 0, v[132:133]
	global_store_dwordx4 v[12:13], v[4:7], off nt
	v_mov_b32_e32 v8, v21
	v_mov_b32_e32 v10, v23
	v_or_b32_e32 v4, v29, v161
	v_add_lshl_u32 v132, s2, v4, 7
	v_lshl_add_u64 v[4:5], v[2:3], 0, v[132:133]
	v_add_u32_e32 v6, 0x400, v163
	global_store_dwordx4 v[4:5], v[8:11], off nt
	ds_read2_b32 v[4:5], v163 offset1:129
	ds_read2_b32 v[6:7], v6 offset0:2 offset1:131
	v_or_b32_e32 v8, v27, v162
	v_add_lshl_u32 v132, s2, v8, 7
	v_lshl_add_u64 v[8:9], v[2:3], 0, v[132:133]
	s_waitcnt lgkmcnt(0)
	global_store_dwordx4 v[8:9], v[4:7], off nt
	ds_read2_b32 v[4:5], v164 offset1:129
	s_nop 0
	v_add_u32_e32 v6, 0x400, v164
	ds_read2_b32 v[6:7], v6 offset0:2 offset1:131
	v_or_b32_e32 v8, v29, v162
	v_add_lshl_u32 v132, s2, v8, 7
	v_lshl_add_u64 v[2:3], v[2:3], 0, v[132:133]
	s_waitcnt lgkmcnt(0)
	global_store_dwordx4 v[2:3], v[4:7], off nt
	s_waitcnt lgkmcnt(0)

.LBB0_94:
	s_waitcnt vmcnt(0)
	v_mul_f32_e32 v6, v6, v18
	v_bfe_u32 v10, v6, 17, 1
	v_mul_f32_e32 v2, v2, v19
	v_add3_u32 v6, v6, v10, s86
	v_bfe_u32 v10, v2, 17, 1
	v_add3_u32 v2, v2, v10, s86
	v_and_b32_e32 v2, 0xfffe0000, v2
	v_and_b32_e32 v6, 0xfffe0000, v6
	v_cvt_pk_bf16_f32 v2, v6, v2
	ds_write_b32 v38, v2 offset:4128
	v_mul_f32_e32 v2, v7, v18
	v_bfe_u32 v6, v2, 17, 1
	v_mul_f32_e32 v3, v3, v19
	v_add3_u32 v2, v2, v6, s86
	v_bfe_u32 v6, v3, 17, 1
	v_and_b32_e32 v2, 0xfffe0000, v2
	v_add3_u32 v3, v3, v6, s86
	v_and_b32_e32 v3, 0xfffe0000, v3
	v_cvt_pk_bf16_f32 v2, v2, v3
	ds_write_b32 v38, v2 offset:4256
	v_mul_f32_e32 v2, v8, v18
	v_bfe_u32 v3, v2, 17, 1
	v_add3_u32 v2, v2, v3, s86
	v_mul_f32_e32 v3, v4, v19
	v_bfe_u32 v4, v3, 17, 1
	v_and_b32_e32 v2, 0xfffe0000, v2
	v_add3_u32 v3, v3, v4, s86
	v_and_b32_e32 v3, 0xfffe0000, v3
	v_cvt_pk_bf16_f32 v2, v2, v3
	ds_write_b32 v38, v2 offset:4384
	v_mul_f32_e32 v2, v9, v18
	v_bfe_u32 v3, v2, 17, 1
	v_add3_u32 v2, v2, v3, s86
	v_mul_f32_e32 v3, v5, v19
	v_bfe_u32 v4, v3, 17, 1
	v_and_b32_e32 v2, 0xfffe0000, v2
	v_add3_u32 v3, v3, v4, s86
	v_and_b32_e32 v3, 0xfffe0000, v3
	v_cvt_pk_bf16_f32 v2, v2, v3
	ds_write_b32 v38, v2 offset:4512
	s_waitcnt lgkmcnt(0)
	ds_read2_b32 v[16:17], v146 offset1:8
	ds_read2_b32 v[4:5], v146 offset0:129 offset1:137
	v_add_u32_e32 v26, 0x400, v146
	ds_read2_b32 v[18:19], v26 offset0:2 offset1:10
	ds_read2_b32 v[6:7], v26 offset0:131 offset1:139
	s_lshl_b32 s38, s2, 7
	s_and_b32 s2, 0xffff, s43
	v_lshlrev_b32_e32 v132, 1, v134
	v_or_b32_e32 v27, s38, v131
	s_mulk_i32 s2, 0x2c00
	v_lshl_add_u64 v[2:3], s[40:41], 0, v[132:133]
	s_mov_b64 s[4:5], 0x5800000
	s_waitcnt lgkmcnt(2)
	v_mov_b32_e32 v9, v4
	v_or_b32_e32 v4, v27, v145
	v_lshl_add_u64 v[2:3], v[2:3], 0, s[4:5]
	v_add_lshl_u32 v132, s2, v4, 7
	v_mov_b32_e32 v8, v16
	s_waitcnt lgkmcnt(1)
	v_mov_b32_e32 v10, v18
	s_waitcnt lgkmcnt(0)
	v_mov_b32_e32 v11, v6
	v_lshl_add_u64 v[12:13], v[2:3], 0, v[132:133]
	global_store_dwordx4 v[12:13], v[8:11], off nt
	v_add_u32_e32 v28, 0x400, v147
	ds_read2_b32 v[20:21], v147 offset1:8
	ds_read2_b32 v[8:9], v147 offset0:129 offset1:137
	ds_read2_b32 v[22:23], v28 offset0:2 offset1:10
	ds_read2_b32 v[10:11], v28 offset0:131 offset1:139
	v_or_b32_e32 v29, s38, v144
	v_or_b32_e32 v4, v29, v145
	v_add_lshl_u32 v132, s2, v4, 7
	s_waitcnt lgkmcnt(3)
	v_mov_b32_e32 v12, v20
	s_waitcnt lgkmcnt(2)
	v_mov_b32_e32 v13, v8
	s_waitcnt lgkmcnt(1)
	v_mov_b32_e32 v14, v22
	s_waitcnt lgkmcnt(0)
	v_mov_b32_e32 v15, v10
	v_lshl_add_u64 v[24:25], v[2:3], 0, v[132:133]
	v_add_u32_e32 v4, 0x400, v149
	global_store_dwordx4 v[24:25], v[12:15], off nt
	ds_read2_b32 v[12:13], v149 offset1:129
	ds_read2_b32 v[14:15], v4 offset0:2 offset1:131
	v_or_b32_e32 v4, v27, v148
	v_add_lshl_u32 v132, s2, v4, 7
	v_lshl_add_u64 v[24:25], v[2:3], 0, v[132:133]
	v_add_u32_e32 v4, 0x400, v150
	s_waitcnt lgkmcnt(0)
	global_store_dwordx4 v[24:25], v[12:15], off nt
	ds_read2_b32 v[12:13], v150 offset1:129
	ds_read2_b32 v[14:15], v4 offset0:2 offset1:131
	v_or_b32_e32 v4, v29, v148
	v_add_lshl_u32 v132, s2, v4, 7
	v_or_b32_e32 v8, v27, v151
	v_lshl_add_u64 v[24:25], v[2:3], 0, v[132:133]
	v_add_lshl_u32 v132, s2, v8, 7
	s_waitcnt lgkmcnt(0)
	global_store_dwordx4 v[24:25], v[12:15], off nt
	v_mov_b32_e32 v4, v17
	v_mov_b32_e32 v6, v19
	v_lshl_add_u64 v[12:13], v[2:3], 0, v[132:133]
	global_store_dwordx4 v[12:13], v[4:7], off nt
	v_mov_b32_e32 v8, v21
	v_mov_b32_e32 v10, v23
	v_or_b32_e32 v4, v29, v151
	v_add_lshl_u32 v132, s2, v4, 7
	v_lshl_add_u64 v[4:5], v[2:3], 0, v[132:133]
	v_add_u32_e32 v6, 0x400, v153
	global_store_dwordx4 v[4:5], v[8:11], off nt
	ds_read2_b32 v[4:5], v153 offset1:129
	ds_read2_b32 v[6:7], v6 offset0:2 offset1:131
	v_or_b32_e32 v8, v27, v152
	v_add_lshl_u32 v132, s2, v8, 7
	v_lshl_add_u64 v[8:9], v[2:3], 0, v[132:133]
	s_waitcnt lgkmcnt(0)
	global_store_dwordx4 v[8:9], v[4:7], off nt
	ds_read2_b32 v[4:5], v154 offset1:129
	s_nop 0
	v_add_u32_e32 v6, 0x400, v154
	ds_read2_b32 v[6:7], v6 offset0:2 offset1:131
	v_or_b32_e32 v8, v29, v152
	v_add_lshl_u32 v132, s2, v8, 7
	v_lshl_add_u64 v[8:9], v[2:3], 0, v[132:133]
	s_waitcnt lgkmcnt(0)
	global_store_dwordx4 v[8:9], v[4:7], off nt
	ds_read2_b32 v[16:17], v146 offset0:16 offset1:24
	ds_read2_b32 v[4:5], v146 offset0:145 offset1:153
	ds_read2_b32 v[18:19], v26 offset0:18 offset1:26
	ds_read2_b32 v[6:7], v26 offset0:147 offset1:155
	s_waitcnt lgkmcnt(3)
	v_mov_b32_e32 v8, v16
	s_waitcnt lgkmcnt(2)
	v_mov_b32_e32 v9, v4
	v_or_b32_e32 v4, v27, v155
	v_add_lshl_u32 v132, s2, v4, 7
	s_waitcnt lgkmcnt(1)
	v_mov_b32_e32 v10, v18
	s_waitcnt lgkmcnt(0)
	v_mov_b32_e32 v11, v6
	v_lshl_add_u64 v[12:13], v[2:3], 0, v[132:133]
	global_store_dwordx4 v[12:13], v[8:11], off nt
	ds_read2_b32 v[20:21], v147 offset0:16 offset1:24
	ds_read2_b32 v[8:9], v147 offset0:145 offset1:153
	ds_read2_b32 v[22:23], v28 offset0:18 offset1:26
	ds_read2_b32 v[10:11], v28 offset0:147 offset1:155
	v_or_b32_e32 v4, v29, v155
	v_add_lshl_u32 v132, s2, v4, 7
	s_waitcnt lgkmcnt(3)
	v_mov_b32_e32 v12, v20
	s_waitcnt lgkmcnt(2)
	v_mov_b32_e32 v13, v8
	s_waitcnt lgkmcnt(1)
	v_mov_b32_e32 v14, v22
	s_waitcnt lgkmcnt(0)
	v_mov_b32_e32 v15, v10
	v_lshl_add_u64 v[24:25], v[2:3], 0, v[132:133]
	v_add_u32_e32 v4, 0x400, v159
	global_store_dwordx4 v[24:25], v[12:15], off nt
	ds_read2_b32 v[12:13], v159 offset1:129
	ds_read2_b32 v[14:15], v4 offset0:2 offset1:131
	v_or_b32_e32 v4, v27, v158
	v_add_lshl_u32 v132, s2, v4, 7
	v_lshl_add_u64 v[24:25], v[2:3], 0, v[132:133]
	v_add_u32_e32 v4, 0x400, v160
	s_waitcnt lgkmcnt(0)
	global_store_dwordx4 v[24:25], v[12:15], off nt
	ds_read2_b32 v[12:13], v160 offset1:129
	ds_read2_b32 v[14:15], v4 offset0:2 offset1:131
	v_or_b32_e32 v4, v29, v158
	v_add_lshl_u32 v132, s2, v4, 7
	v_or_b32_e32 v8, v27, v161
	v_lshl_add_u64 v[24:25], v[2:3], 0, v[132:133]
	v_add_lshl_u32 v132, s2, v8, 7
	s_waitcnt lgkmcnt(0)
	global_store_dwordx4 v[24:25], v[12:15], off nt
	v_mov_b32_e32 v4, v17
	v_mov_b32_e32 v6, v19
	v_lshl_add_u64 v[12:13], v[2:3], 0, v[132:133]
	global_store_dwordx4 v[12:13], v[4:7], off nt
	v_mov_b32_e32 v8, v21
	v_mov_b32_e32 v10, v23
	v_or_b32_e32 v4, v29, v161
	v_add_lshl_u32 v132, s2, v4, 7
	v_lshl_add_u64 v[4:5], v[2:3], 0, v[132:133]
	v_add_u32_e32 v6, 0x400, v163
	global_store_dwordx4 v[4:5], v[8:11], off nt
	ds_read2_b32 v[4:5], v163 offset1:129
	ds_read2_b32 v[6:7], v6 offset0:2 offset1:131
	v_or_b32_e32 v8, v27, v162
	v_add_lshl_u32 v132, s2, v8, 7
	v_lshl_add_u64 v[8:9], v[2:3], 0, v[132:133]
	s_waitcnt lgkmcnt(0)
	global_store_dwordx4 v[8:9], v[4:7], off nt
	ds_read2_b32 v[4:5], v164 offset1:129
	s_nop 0
	v_add_u32_e32 v6, 0x400, v164
	ds_read2_b32 v[6:7], v6 offset0:2 offset1:131
	v_or_b32_e32 v8, v29, v162
	v_add_lshl_u32 v132, s2, v8, 7
	v_lshl_add_u64 v[2:3], v[2:3], 0, v[132:133]
	s_waitcnt lgkmcnt(0)
	global_store_dwordx4 v[2:3], v[4:7], off nt
	s_waitcnt lgkmcnt(0)

.LBB0_635:
	s_or_b64 exec, exec, s[10:11]
	v_lshl_add_u64 v[20:21], s[2:3], 0, v[10:11]
	v_add_co_u32_e32 v28, vcc, s12, v20
	s_nop 1
	v_addc_co_u32_e32 v29, vcc, 0, v21, vcc
	global_load_dwordx4 v[224:227], v[28:29], off nt
	global_load_dwordx4 v[228:231], v[28:29], off offset:1024 nt
	global_load_dwordx4 v[232:235], v[28:29], off offset:2048 nt
	global_load_dwordx4 v[236:239], v[28:29], off offset:3072 nt
	s_waitcnt vmcnt(4)
	v_add_f32_dpp v18, v18, v18 row_shr:1 row_mask:0xf bank_mask:0xf bound_ctrl:1
	s_nop 1
	v_add_f32_dpp v18, v18, v18 row_shr:2 row_mask:0xf bank_mask:0xf bound_ctrl:1
	v_mov_b32_e32 v19, 0
	v_mov_b32_e32 v32, 0
	v_add_f32_dpp v18, v18, v18 row_shr:4 row_mask:0xf bank_mask:0xf bound_ctrl:1
	v_add_co_u32_e32 v30, vcc, s13, v12
	s_nop 0
	v_add_f32_dpp v18, v18, v18 row_shr:8 row_mask:0xf bank_mask:0xf bound_ctrl:1
	v_addc_co_u32_e32 v31, vcc, -1, v13, vcc
	s_nop 0
	v_mov_b32_dpp v19, v18 row_bcast:15 row_mask:0xa bank_mask:0xf
	v_add_f32_e32 v18, v18, v19
	v_lshl_add_u64 v[10:11], v[10:11], 0, s[4:5]
	v_lshl_add_u64 v[14:15], v[14:15], 0, s[8:9]
	v_mov_b32_dpp v32, v18 row_bcast:31 row_mask:0xc bank_mask:0xf
	v_add_f32_e32 v18, v18, v32
	s_waitcnt vmcnt(3)
	v_mov_b32_e32 v20, v224
	v_mov_b32_e32 v21, v225
	v_mov_b32_e32 v22, v226
	v_mov_b32_e32 v23, v227
	v_and_b32_e32 v19, 0xffff0000, v20
	v_readlane_b32 s10, v18, 63
	s_nop 1
	v_fma_f32 v18, s10, v17, v16
	v_rsq_f32_e32 v32, v18
	v_lshlrev_b32_e32 v18, 16, v20
	v_lshlrev_b32_e32 v20, 16, v21
	v_and_b32_e32 v21, 0xffff0000, v21
	v_pk_mul_f32 v[18:19], v[32:33], v[18:19] op_sel_hi:[0,1]
	v_pk_mul_f32 v[20:21], v[32:33], v[20:21] op_sel_hi:[0,1]
	v_mov_b32_e32 v24, v192
	v_mov_b32_e32 v25, v193
	v_mov_b32_e32 v26, v194
	v_mov_b32_e32 v27, v195
	v_pk_mul_f32 v[20:21], v[26:27], v[20:21]
	v_pk_mul_f32 v[18:19], v[24:25], v[18:19]
	global_store_dwordx4 v[30:31], v[18:21], off offset:-2064 nt
	v_lshlrev_b32_e32 v24, 16, v22
	v_and_b32_e32 v25, 0xffff0000, v22
	v_lshlrev_b32_e32 v22, 16, v23
	v_and_b32_e32 v23, 0xffff0000, v23
	v_pk_mul_f32 v[22:23], v[32:33], v[22:23] op_sel_hi:[0,1]
	v_pk_mul_f32 v[24:25], v[32:33], v[24:25] op_sel_hi:[0,1]
	s_add_i32 s10, s16, s18
	s_mov_b32 s16, s10
	s_cmpk_gt_i32 s10, 0x3fff
	v_mov_b32_e32 v18, v196
	v_mov_b32_e32 v19, v197
	v_mov_b32_e32 v20, v198
	v_mov_b32_e32 v21, v199
	v_pk_mul_f32 v[18:19], v[18:19], v[24:25]
	v_pk_mul_f32 v[20:21], v[20:21], v[22:23]
	global_store_dwordx4 v[30:31], v[18:21], off offset:-2048 nt
	s_nop 1
	s_waitcnt vmcnt(4)
	v_mov_b32_e32 v18, v228
	v_mov_b32_e32 v19, v229
	v_mov_b32_e32 v20, v230
	v_mov_b32_e32 v21, v231
	v_mov_b32_e32 v22, v200
	v_mov_b32_e32 v23, v201
	v_mov_b32_e32 v24, v202
	v_mov_b32_e32 v25, v203
	v_lshlrev_b32_e32 v26, 16, v18
	v_and_b32_e32 v27, 0xffff0000, v18
	v_lshlrev_b32_e32 v18, 16, v19
	v_and_b32_e32 v19, 0xffff0000, v19
	v_pk_mul_f32 v[26:27], v[32:33], v[26:27] op_sel_hi:[0,1]
	v_pk_mul_f32 v[18:19], v[32:33], v[18:19] op_sel_hi:[0,1]
	v_pk_mul_f32 v[24:25], v[24:25], v[18:19]
	v_pk_mul_f32 v[22:23], v[22:23], v[26:27]
	global_store_dwordx4 v[30:31], v[22:25], off offset:-16 nt
	s_nop 1
	v_mov_b32_e32 v22, v204
	v_mov_b32_e32 v23, v205
	v_mov_b32_e32 v24, v206
	v_mov_b32_e32 v25, v207
	v_lshlrev_b32_e32 v18, 16, v20
	v_and_b32_e32 v19, 0xffff0000, v20
	v_lshlrev_b32_e32 v20, 16, v21
	v_and_b32_e32 v21, 0xffff0000, v21
	v_pk_mul_f32 v[20:21], v[32:33], v[20:21] op_sel_hi:[0,1]
	v_pk_mul_f32 v[18:19], v[32:33], v[18:19] op_sel_hi:[0,1]
	v_pk_mul_f32 v[18:19], v[22:23], v[18:19]
	v_pk_mul_f32 v[20:21], v[24:25], v[20:21]
	global_store_dwordx4 v[12:13], v[18:21], off offset:-4096 nt
	s_nop 1
	s_waitcnt vmcnt(5)
	v_mov_b32_e32 v18, v232
	v_mov_b32_e32 v19, v233
	v_mov_b32_e32 v20, v234
	v_mov_b32_e32 v21, v235
	v_mov_b32_e32 v22, v208
	v_mov_b32_e32 v23, v209
	v_mov_b32_e32 v24, v210
	v_mov_b32_e32 v25, v211
	v_lshlrev_b32_e32 v26, 16, v18
	v_and_b32_e32 v27, 0xffff0000, v18
	v_lshlrev_b32_e32 v18, 16, v19
	v_and_b32_e32 v19, 0xffff0000, v19
	v_pk_mul_f32 v[26:27], v[32:33], v[26:27] op_sel_hi:[0,1]
	v_pk_mul_f32 v[18:19], v[32:33], v[18:19] op_sel_hi:[0,1]
	v_pk_mul_f32 v[24:25], v[24:25], v[18:19]
	v_pk_mul_f32 v[22:23], v[22:23], v[26:27]
	global_store_dwordx4 v[12:13], v[22:25], off offset:-2064 nt
	s_nop 1
	v_mov_b32_e32 v22, v212
	v_mov_b32_e32 v23, v213
	v_mov_b32_e32 v24, v214
	v_mov_b32_e32 v25, v215
	v_lshlrev_b32_e32 v18, 16, v20
	v_and_b32_e32 v19, 0xffff0000, v20
	v_lshlrev_b32_e32 v20, 16, v21
	v_and_b32_e32 v21, 0xffff0000, v21
	v_pk_mul_f32 v[20:21], v[32:33], v[20:21] op_sel_hi:[0,1]
	v_pk_mul_f32 v[18:19], v[32:33], v[18:19] op_sel_hi:[0,1]
	v_pk_mul_f32 v[18:19], v[22:23], v[18:19]
	v_pk_mul_f32 v[20:21], v[24:25], v[20:21]
	global_store_dwordx4 v[12:13], v[18:21], off offset:-2048 nt
	s_nop 1
	s_waitcnt vmcnt(6)
	v_mov_b32_e32 v18, v236
	v_mov_b32_e32 v19, v237
	v_mov_b32_e32 v20, v238
	v_mov_b32_e32 v21, v239
	v_mov_b32_e32 v22, v216
	v_mov_b32_e32 v23, v217
	v_mov_b32_e32 v24, v218
	v_mov_b32_e32 v25, v219
	v_lshlrev_b32_e32 v26, 16, v18
	v_and_b32_e32 v27, 0xffff0000, v18
	v_lshlrev_b32_e32 v18, 16, v19
	v_and_b32_e32 v19, 0xffff0000, v19
	v_pk_mul_f32 v[26:27], v[32:33], v[26:27] op_sel_hi:[0,1]
	v_pk_mul_f32 v[18:19], v[32:33], v[18:19] op_sel_hi:[0,1]
	v_pk_mul_f32 v[24:25], v[24:25], v[18:19]
	v_pk_mul_f32 v[22:23], v[22:23], v[26:27]
	global_store_dwordx4 v[12:13], v[22:25], off offset:-16 nt
	s_nop 1
	v_mov_b32_e32 v22, v220
	v_mov_b32_e32 v23, v221
	v_mov_b32_e32 v24, v222
	v_mov_b32_e32 v25, v223
	v_lshlrev_b32_e32 v18, 16, v20
	v_and_b32_e32 v19, 0xffff0000, v20
	v_lshlrev_b32_e32 v20, 16, v21
	v_and_b32_e32 v21, 0xffff0000, v21
	v_pk_mul_f32 v[20:21], v[32:33], v[20:21] op_sel_hi:[0,1]
	v_pk_mul_f32 v[18:19], v[32:33], v[18:19] op_sel_hi:[0,1]
	v_pk_mul_f32 v[18:19], v[22:23], v[18:19]
	v_pk_mul_f32 v[20:21], v[24:25], v[20:21]
	global_store_dwordx4 v[12:13], v[18:21], off nt
	v_lshl_add_u64 v[12:13], v[12:13], 0, s[6:7]
	s_cbranch_scc1 .LBB0_638
